# cache policy: the 45 P0 write-once bf16 stores (weights, x rows, p) as device-scope write-through (sc1 nt) so the grid-sync wbl2 has nothing left to flush; on top of v034
# baseline (speedup 1.0000x reference)
; #define LAS __attribute__((address_space(3)))
; __device__ __forceinline__ unsigned pk2(float lo, float hi) { return f2bf(lo) | (f2bf(hi) << 16); }
; __device__ __forceinline__ void cv_process(const CvDesc& d, int lane, const f32x4 (&v)[16], const f32x4& g0, const f32x4& g1, LAS float* scr) {
;     ...
;     for (int j = 0; j < 8; ++j) { const int n = (lane >> 3) + 8 * j; const LAS float* s = scr + (8 * c) * 64 + (n ^ (8 * c));
;         u32x4 o; o.x = pk2(s[0 * 64] * g0[0], s[1 * 64] * g0[1]); o.y = pk2(s[2 * 64] * g0[2], s[3 * 64] * g0[3]); o.z = pk2(s[4 * 64] * g1[0], s[5 * 64] * g1[1]); o.w = pk2(s[6 * 64] * g1[2], s[7 * 64] * g1[3]);
;         const int ng = n0 + n, drow = d.mode ? (((ng >> 7) << 8) + (ng & 127) + d.off) : (d.off + ng);
;         *(u32x4*)(d.dst + (size_t)drow * d.K + k0 + 8 * c) = o; }
.Lcv_ladB_done:
	v_ashrrev_i32_e32 v164, 31, v205
	s_waitcnt lgkmcnt(0)
	v_mul_f32_e32 v5, 0x4f7ffffe, v5
	v_cvt_u32_f32_e32 v5, v5
	v_mul_lo_u32 v166, v166, v5
	v_mul_hi_u32 v166, v5, v166
	v_add_u32_e32 v5, v5, v166
	v_mul_hi_u32 v5, v165, v5
	v_mul_lo_u32 v166, v5, v4
	v_sub_u32_e32 v165, v165, v166
	v_add_u32_e32 v167, 1, v5
	v_cmp_ge_u32_e64 s[4:5], v165, v4
	v_sub_u32_e32 v166, v165, v4
	s_nop 0
	v_cndmask_b32_e64 v5, v5, v167, s[4:5]
	v_cndmask_b32_e64 v165, v165, v166, s[4:5]
	v_add_u32_e32 v166, 1, v5
	v_cmp_ge_u32_e64 s[4:5], v165, v4
	s_nop 1
	v_cndmask_b32_e64 v5, v5, v166, s[4:5]
	v_xor_b32_e32 v5, v5, v164
	v_sub_u32_e32 v5, v5, v164
	ds_read2st64_b32 v[164:165], v185 offset1:1
	ds_read2st64_b32 v[168:169], v185 offset0:2 offset1:3
	v_mul_lo_u32 v4, v5, v4
	ds_read2st64_b32 v[208:209], v185 offset0:4 offset1:5
	ds_read2st64_b32 v[210:211], v185 offset0:6 offset1:7
	v_sub_u32_e32 v4, v205, v4
	v_lshlrev_b32_e32 v206, 6, v4
	v_lshlrev_b32_e32 v4, 7, v4
	v_lshlrev_b32_e32 v170, 6, v5
	v_and_b32_e32 v207, 0xffffff00, v4
	v_mov_b32_e32 v4, v142
	v_mov_b32_e32 v5, v144
	s_waitcnt lgkmcnt(3)
	v_mov_b32_e32 v166, v164
	s_waitcnt lgkmcnt(2)
	v_mov_b32_e32 v167, v168
	v_pk_mul_f32 v[212:213], v[4:5], v[166:167]
	v_mov_b32_e32 v166, v143
	v_mov_b32_e32 v167, v145
	v_mov_b32_e32 v168, v165
	v_pk_mul_f32 v[214:215], v[166:167], v[168:169]
	v_mov_b32_e32 v164, v146
	v_mov_b32_e32 v165, v148
	s_waitcnt lgkmcnt(1)
	v_mov_b32_e32 v168, v208
	s_waitcnt lgkmcnt(0)
	v_mov_b32_e32 v169, v210
	v_pk_mul_f32 v[216:217], v[164:165], v[168:169]
	v_mov_b32_e32 v168, v147
	v_mov_b32_e32 v169, v149
	v_mov_b32_e32 v210, v209
	v_pk_mul_f32 v[208:209], v[168:169], v[210:211]
	v_bfe_u32 v218, v215, 16, 1
	v_bfe_u32 v210, v209, 16, 1
	v_bfe_u32 v211, v208, 16, 1
	v_bfe_u32 v219, v214, 16, 1
	v_add3_u32 v215, v215, v218, s55
	v_add3_u32 v209, v209, v210, s55
	v_bfe_u32 v210, v212, 16, 1
	v_bfe_u32 v218, v216, 16, 1
	v_add3_u32 v214, v214, v219, s55
	v_add3_u32 v208, v208, v211, s55
	v_bfe_u32 v211, v213, 16, 1
	v_bfe_u32 v219, v217, 16, 1
	v_add3_u32 v216, v216, v218, s55
	v_add3_u32 v210, v212, v210, s55
	v_add3_u32 v217, v217, v219, s55
	v_add3_u32 v211, v213, v211, s55
	v_lshrrev_b32_e32 v212, 16, v210
	v_lshrrev_b32_e32 v210, 16, v216
	v_lshrrev_b32_e32 v213, 16, v211
	v_lshrrev_b32_e32 v211, 16, v217
	v_and_or_b32 v210, v208, s56, v210
	v_and_or_b32 v208, v214, s56, v212
	v_or_b32_e32 v212, v206, v184
	v_and_or_b32 v211, v209, s56, v211
	v_and_or_b32 v209, v215, s56, v213
	v_and_or_b32 v213, v212, s57, v207
	v_cmp_eq_u32_e64 s[4:5], 0, v203
	v_ashrrev_i32_e32 v171, 31, v170
	v_lshlrev_b64 v[170:171], 1, v[170:171]
	v_cndmask_b32_e64 v212, v213, v212, s[4:5]
	v_add_u32_e32 v212, v212, v204
	v_ashrrev_i32_e32 v215, 31, v212
	v_mad_u64_u32 v[212:213], s[0:1], v212, v202, 0
	v_mov_b32_e32 v214, v213
	v_mad_u64_u32 v[214:215], s[0:1], v215, v202, v[214:215]
	v_mov_b32_e32 v213, v214
	v_lshl_add_u64 v[212:213], v[212:213], 1, v[160:161]
	v_lshl_add_u64 v[212:213], v[212:213], 0, v[170:171]
	v_lshl_add_u64 v[212:213], v[212:213], 0, v[162:163]
	ds_read2st64_b32 v[214:215], v187 offset1:1
	ds_read2st64_b32 v[216:217], v187 offset0:2 offset1:3
	global_store_dwordx4 v[212:213], v[208:211], off sc1 nt
	ds_read2st64_b32 v[208:209], v187 offset0:4 offset1:5
	ds_read2st64_b32 v[210:211], v187 offset0:6 offset1:7
	s_waitcnt lgkmcnt(3)
	v_mov_b32_e32 v212, v214
	s_waitcnt lgkmcnt(2)
	v_mov_b32_e32 v213, v216
	v_mov_b32_e32 v216, v215
	v_pk_mul_f32 v[214:215], v[166:167], v[216:217]
	s_waitcnt lgkmcnt(0)
	v_mov_b32_e32 v217, v210
	v_mov_b32_e32 v210, v209
	v_mov_b32_e32 v216, v208
	v_pk_mul_f32 v[208:209], v[168:169], v[210:211]
	v_pk_mul_f32 v[212:213], v[4:5], v[212:213]
	v_pk_mul_f32 v[216:217], v[164:165], v[216:217]
	v_bfe_u32 v210, v209, 16, 1
	v_bfe_u32 v218, v215, 16, 1
	v_bfe_u32 v211, v208, 16, 1
	v_bfe_u32 v219, v214, 16, 1
	v_add3_u32 v215, v215, v218, s55
	v_add3_u32 v209, v209, v210, s55
	v_bfe_u32 v210, v212, 16, 1
	v_bfe_u32 v218, v216, 16, 1
	v_add3_u32 v214, v214, v219, s55
	v_add3_u32 v208, v208, v211, s55
	v_bfe_u32 v211, v213, 16, 1
	v_bfe_u32 v219, v217, 16, 1
	v_add3_u32 v216, v216, v218, s55
	v_add3_u32 v210, v212, v210, s55
	v_add3_u32 v217, v217, v219, s55
	v_add3_u32 v211, v213, v211, s55
	v_lshrrev_b32_e32 v212, 16, v210
	v_lshrrev_b32_e32 v210, 16, v216
	v_lshrrev_b32_e32 v213, 16, v211
	v_lshrrev_b32_e32 v211, 16, v217
	v_and_or_b32 v210, v208, s56, v210
	v_and_or_b32 v208, v214, s56, v212
	v_or_b32_e32 v212, v206, v186
	v_and_or_b32 v211, v209, s56, v211
	v_and_or_b32 v209, v215, s56, v213
	v_and_or_b32 v213, v212, s62, v207
	v_cndmask_b32_e64 v212, v213, v212, s[4:5]
	v_add_u32_e32 v212, v212, v204
	v_ashrrev_i32_e32 v215, 31, v212
	v_mad_u64_u32 v[212:213], s[0:1], v212, v202, 0
	v_mov_b32_e32 v214, v213
	v_mad_u64_u32 v[214:215], s[0:1], v215, v202, v[214:215]
	v_mov_b32_e32 v213, v214
	v_lshl_add_u64 v[212:213], v[212:213], 1, v[160:161]
	v_lshl_add_u64 v[212:213], v[212:213], 0, v[170:171]
	v_lshl_add_u64 v[212:213], v[212:213], 0, v[162:163]
	ds_read2st64_b32 v[214:215], v189 offset1:1
	ds_read2st64_b32 v[216:217], v189 offset0:2 offset1:3
	global_store_dwordx4 v[212:213], v[208:211], off sc1 nt
	ds_read2st64_b32 v[208:209], v189 offset0:4 offset1:5
	ds_read2st64_b32 v[210:211], v189 offset0:6 offset1:7
	s_waitcnt lgkmcnt(3)
	v_mov_b32_e32 v212, v214
	s_waitcnt lgkmcnt(2)
	v_mov_b32_e32 v213, v216
	v_mov_b32_e32 v216, v215
	v_pk_mul_f32 v[214:215], v[166:167], v[216:217]
	s_waitcnt lgkmcnt(0)
; #define LAS __attribute__((address_space(3)))
; __device__ __forceinline__ unsigned pk2(float lo, float hi) { return f2bf(lo) | (f2bf(hi) << 16); }
; __device__ __forceinline__ void cv_process(const CvDesc& d, int lane, const f32x4 (&v)[16], const f32x4& g0, const f32x4& g1, LAS float* scr) {
;     ...
;     for (int j = 0; j < 8; ++j) { const int n = (lane >> 3) + 8 * j; const LAS float* s = scr + (8 * c) * 64 + (n ^ (8 * c));
;         u32x4 o; o.x = pk2(s[0 * 64] * g0[0], s[1 * 64] * g0[1]); o.y = pk2(s[2 * 64] * g0[2], s[3 * 64] * g0[3]); o.z = pk2(s[4 * 64] * g1[0], s[5 * 64] * g1[1]); o.w = pk2(s[6 * 64] * g1[2], s[7 * 64] * g1[3]);
;         const int ng = n0 + n, drow = d.mode ? (((ng >> 7) << 8) + (ng & 127) + d.off) : (d.off + ng);
;         *(u32x4*)(d.dst + (size_t)drow * d.K + k0 + 8 * c) = o; }
	v_mov_b32_e32 v217, v210
	v_mov_b32_e32 v210, v209
	v_mov_b32_e32 v216, v208
	v_pk_mul_f32 v[208:209], v[168:169], v[210:211]
	v_pk_mul_f32 v[212:213], v[4:5], v[212:213]
	v_pk_mul_f32 v[216:217], v[164:165], v[216:217]
	v_bfe_u32 v210, v209, 16, 1
	v_bfe_u32 v218, v215, 16, 1
	v_bfe_u32 v211, v208, 16, 1
	v_bfe_u32 v219, v214, 16, 1
	v_add3_u32 v215, v215, v218, s55
	v_add3_u32 v209, v209, v210, s55
	v_bfe_u32 v210, v212, 16, 1
	v_bfe_u32 v218, v216, 16, 1
	v_add3_u32 v214, v214, v219, s55
	v_add3_u32 v208, v208, v211, s55
	v_bfe_u32 v211, v213, 16, 1
	v_bfe_u32 v219, v217, 16, 1
	v_add3_u32 v216, v216, v218, s55
	v_add3_u32 v210, v212, v210, s55
	v_add3_u32 v217, v217, v219, s55
	v_add3_u32 v211, v213, v211, s55
	v_lshrrev_b32_e32 v212, 16, v210
	v_lshrrev_b32_e32 v210, 16, v216
	v_lshrrev_b32_e32 v213, 16, v211
	v_lshrrev_b32_e32 v211, 16, v217
	v_and_or_b32 v210, v208, s56, v210
	v_and_or_b32 v208, v214, s56, v212
	v_or_b32_e32 v212, v206, v188
	v_and_or_b32 v211, v209, s56, v211
	v_and_or_b32 v209, v215, s56, v213
	v_and_or_b32 v213, v212, s63, v207
	v_cndmask_b32_e64 v212, v213, v212, s[4:5]
	v_add_u32_e32 v212, v212, v204
	v_ashrrev_i32_e32 v215, 31, v212
	v_mad_u64_u32 v[212:213], s[0:1], v212, v202, 0
	v_mov_b32_e32 v214, v213
	v_mad_u64_u32 v[214:215], s[0:1], v215, v202, v[214:215]
	v_mov_b32_e32 v213, v214
	v_lshl_add_u64 v[212:213], v[212:213], 1, v[160:161]
	v_lshl_add_u64 v[212:213], v[212:213], 0, v[170:171]
	v_lshl_add_u64 v[212:213], v[212:213], 0, v[162:163]
	ds_read2st64_b32 v[214:215], v191 offset1:1
	ds_read2st64_b32 v[216:217], v191 offset0:2 offset1:3
	global_store_dwordx4 v[212:213], v[208:211], off sc1 nt
	ds_read2st64_b32 v[208:209], v191 offset0:4 offset1:5
	ds_read2st64_b32 v[210:211], v191 offset0:6 offset1:7
	s_waitcnt lgkmcnt(3)
	v_mov_b32_e32 v212, v214
	s_waitcnt lgkmcnt(2)
	v_mov_b32_e32 v213, v216
	v_mov_b32_e32 v216, v215
	v_pk_mul_f32 v[214:215], v[166:167], v[216:217]
	s_waitcnt lgkmcnt(0)
	v_mov_b32_e32 v217, v210
	v_mov_b32_e32 v210, v209
	v_mov_b32_e32 v216, v208
	v_pk_mul_f32 v[208:209], v[168:169], v[210:211]
	v_pk_mul_f32 v[212:213], v[4:5], v[212:213]
	v_pk_mul_f32 v[216:217], v[164:165], v[216:217]
	v_bfe_u32 v210, v209, 16, 1
	v_bfe_u32 v218, v215, 16, 1
	v_bfe_u32 v211, v208, 16, 1
	v_bfe_u32 v219, v214, 16, 1
	v_add3_u32 v215, v215, v218, s55
	v_add3_u32 v209, v209, v210, s55
	v_bfe_u32 v210, v212, 16, 1
	v_bfe_u32 v218, v216, 16, 1
	v_add3_u32 v214, v214, v219, s55
	v_add3_u32 v208, v208, v211, s55
	v_bfe_u32 v211, v213, 16, 1
	v_bfe_u32 v219, v217, 16, 1
	v_add3_u32 v216, v216, v218, s55
	v_add3_u32 v210, v212, v210, s55
	v_add3_u32 v217, v217, v219, s55
	v_add3_u32 v211, v213, v211, s55
	v_lshrrev_b32_e32 v212, 16, v210
	v_lshrrev_b32_e32 v210, 16, v216
	v_lshrrev_b32_e32 v213, 16, v211
	v_lshrrev_b32_e32 v211, 16, v217
	v_and_or_b32 v210, v208, s56, v210
	v_and_or_b32 v208, v214, s56, v212
	v_or_b32_e32 v212, v206, v190
	v_and_or_b32 v211, v209, s56, v211
	v_and_or_b32 v209, v215, s56, v213
	v_and_or_b32 v213, v212, s64, v207
	v_cndmask_b32_e64 v212, v213, v212, s[4:5]
	v_add_u32_e32 v212, v212, v204
	v_ashrrev_i32_e32 v215, 31, v212
	v_mad_u64_u32 v[212:213], s[0:1], v212, v202, 0
	v_mov_b32_e32 v214, v213
	v_mad_u64_u32 v[214:215], s[0:1], v215, v202, v[214:215]
	v_mov_b32_e32 v213, v214
	v_lshl_add_u64 v[212:213], v[212:213], 1, v[160:161]
	v_lshl_add_u64 v[212:213], v[212:213], 0, v[170:171]
	v_lshl_add_u64 v[212:213], v[212:213], 0, v[162:163]
	ds_read2st64_b32 v[214:215], v193 offset1:1
	ds_read2st64_b32 v[216:217], v193 offset0:2 offset1:3
	global_store_dwordx4 v[212:213], v[208:211], off sc1 nt
	ds_read2st64_b32 v[208:209], v193 offset0:4 offset1:5
	ds_read2st64_b32 v[210:211], v193 offset0:6 offset1:7
	s_waitcnt lgkmcnt(3)
	v_mov_b32_e32 v212, v214
	s_waitcnt lgkmcnt(2)
	v_mov_b32_e32 v213, v216
	v_mov_b32_e32 v216, v215
	v_pk_mul_f32 v[214:215], v[166:167], v[216:217]
	s_waitcnt lgkmcnt(0)
	v_mov_b32_e32 v217, v210
	v_mov_b32_e32 v210, v209
	v_mov_b32_e32 v216, v208
	v_pk_mul_f32 v[208:209], v[168:169], v[210:211]
	v_pk_mul_f32 v[212:213], v[4:5], v[212:213]
	v_pk_mul_f32 v[216:217], v[164:165], v[216:217]
	v_bfe_u32 v210, v209, 16, 1
	v_bfe_u32 v218, v215, 16, 1
	v_bfe_u32 v211, v208, 16, 1
	v_bfe_u32 v219, v214, 16, 1
	v_add3_u32 v215, v215, v218, s55
	v_add3_u32 v209, v209, v210, s55
	v_bfe_u32 v210, v212, 16, 1
	v_bfe_u32 v218, v216, 16, 1
	v_add3_u32 v214, v214, v219, s55
	v_add3_u32 v208, v208, v211, s55
	v_bfe_u32 v211, v213, 16, 1
	v_bfe_u32 v219, v217, 16, 1
	v_add3_u32 v216, v216, v218, s55
	v_add3_u32 v210, v212, v210, s55
	v_add3_u32 v217, v217, v219, s55
	v_add3_u32 v211, v213, v211, s55
	v_lshrrev_b32_e32 v212, 16, v210
	v_lshrrev_b32_e32 v210, 16, v216
	v_lshrrev_b32_e32 v213, 16, v211
	v_lshrrev_b32_e32 v211, 16, v217
	v_and_or_b32 v210, v208, s56, v210
	v_and_or_b32 v208, v214, s56, v212
	v_or_b32_e32 v212, v206, v192
	v_and_or_b32 v211, v209, s56, v211
	v_and_or_b32 v209, v215, s56, v213
	v_and_or_b32 v213, v212, s65, v207
	v_cndmask_b32_e64 v212, v213, v212, s[4:5]
	v_add_u32_e32 v212, v212, v204
	v_ashrrev_i32_e32 v215, 31, v212
	v_mad_u64_u32 v[212:213], s[0:1], v212, v202, 0
	v_mov_b32_e32 v214, v213
	v_mad_u64_u32 v[214:215], s[0:1], v215, v202, v[214:215]
	v_mov_b32_e32 v213, v214
	v_lshl_add_u64 v[212:213], v[212:213], 1, v[160:161]
	v_lshl_add_u64 v[212:213], v[212:213], 0, v[170:171]
	v_lshl_add_u64 v[212:213], v[212:213], 0, v[162:163]
	ds_read2st64_b32 v[214:215], v195 offset1:1
	ds_read2st64_b32 v[216:217], v195 offset0:2 offset1:3
	global_store_dwordx4 v[212:213], v[208:211], off sc1 nt
	ds_read2st64_b32 v[208:209], v195 offset0:4 offset1:5
	ds_read2st64_b32 v[210:211], v195 offset0:6 offset1:7
	s_waitcnt lgkmcnt(3)
; #define LAS __attribute__((address_space(3)))
; __device__ __forceinline__ unsigned pk2(float lo, float hi) { return f2bf(lo) | (f2bf(hi) << 16); }
; __device__ __forceinline__ void cv_process(const CvDesc& d, int lane, const f32x4 (&v)[16], const f32x4& g0, const f32x4& g1, LAS float* scr) {
;     ...
;     for (int j = 0; j < 8; ++j) { const int n = (lane >> 3) + 8 * j; const LAS float* s = scr + (8 * c) * 64 + (n ^ (8 * c));
;         u32x4 o; o.x = pk2(s[0 * 64] * g0[0], s[1 * 64] * g0[1]); o.y = pk2(s[2 * 64] * g0[2], s[3 * 64] * g0[3]); o.z = pk2(s[4 * 64] * g1[0], s[5 * 64] * g1[1]); o.w = pk2(s[6 * 64] * g1[2], s[7 * 64] * g1[3]);
;         const int ng = n0 + n, drow = d.mode ? (((ng >> 7) << 8) + (ng & 127) + d.off) : (d.off + ng);
;         *(u32x4*)(d.dst + (size_t)drow * d.K + k0 + 8 * c) = o; }
	v_mov_b32_e32 v212, v214
	s_waitcnt lgkmcnt(2)
	v_mov_b32_e32 v213, v216
	v_mov_b32_e32 v216, v215
	v_pk_mul_f32 v[214:215], v[166:167], v[216:217]
	s_waitcnt lgkmcnt(0)
	v_mov_b32_e32 v217, v210
	v_mov_b32_e32 v210, v209
	v_mov_b32_e32 v216, v208
	v_pk_mul_f32 v[208:209], v[168:169], v[210:211]
	v_pk_mul_f32 v[212:213], v[4:5], v[212:213]
	v_pk_mul_f32 v[216:217], v[164:165], v[216:217]
	v_bfe_u32 v210, v209, 16, 1
	v_bfe_u32 v218, v215, 16, 1
	v_bfe_u32 v211, v208, 16, 1
	v_bfe_u32 v219, v214, 16, 1
	v_add3_u32 v215, v215, v218, s55
	v_add3_u32 v209, v209, v210, s55
	v_bfe_u32 v210, v212, 16, 1
	v_bfe_u32 v218, v216, 16, 1
	v_add3_u32 v214, v214, v219, s55
	v_add3_u32 v208, v208, v211, s55
	v_bfe_u32 v211, v213, 16, 1
	v_bfe_u32 v219, v217, 16, 1
	v_add3_u32 v216, v216, v218, s55
	v_add3_u32 v210, v212, v210, s55
	v_add3_u32 v217, v217, v219, s55
	v_add3_u32 v211, v213, v211, s55
	v_lshrrev_b32_e32 v212, 16, v210
	v_lshrrev_b32_e32 v210, 16, v216
	v_lshrrev_b32_e32 v213, 16, v211
	v_lshrrev_b32_e32 v211, 16, v217
	v_and_or_b32 v210, v208, s56, v210
	v_and_or_b32 v208, v214, s56, v212
	v_or_b32_e32 v212, v206, v194
	v_and_or_b32 v211, v209, s56, v211
	v_and_or_b32 v209, v215, s56, v213
	v_and_or_b32 v213, v212, s66, v207
	v_cndmask_b32_e64 v212, v213, v212, s[4:5]
	v_add_u32_e32 v212, v212, v204
	v_ashrrev_i32_e32 v215, 31, v212
	v_mad_u64_u32 v[212:213], s[0:1], v212, v202, 0
	v_mov_b32_e32 v214, v213
	v_mad_u64_u32 v[214:215], s[0:1], v215, v202, v[214:215]
	v_mov_b32_e32 v213, v214
	v_lshl_add_u64 v[212:213], v[212:213], 1, v[160:161]
	v_lshl_add_u64 v[212:213], v[212:213], 0, v[170:171]
	v_lshl_add_u64 v[212:213], v[212:213], 0, v[162:163]
	ds_read2st64_b32 v[214:215], v197 offset1:1
	ds_read2st64_b32 v[216:217], v197 offset0:2 offset1:3
	global_store_dwordx4 v[212:213], v[208:211], off sc1 nt
	ds_read2st64_b32 v[208:209], v197 offset0:4 offset1:5
	ds_read2st64_b32 v[210:211], v197 offset0:6 offset1:7
	s_waitcnt lgkmcnt(3)
	v_mov_b32_e32 v212, v214
	s_waitcnt lgkmcnt(2)
	v_mov_b32_e32 v213, v216
	v_mov_b32_e32 v216, v215
	v_pk_mul_f32 v[214:215], v[166:167], v[216:217]
	s_waitcnt lgkmcnt(0)
	v_mov_b32_e32 v217, v210
	v_mov_b32_e32 v210, v209
	v_mov_b32_e32 v216, v208
	v_pk_mul_f32 v[208:209], v[168:169], v[210:211]
	v_pk_mul_f32 v[212:213], v[4:5], v[212:213]
	v_pk_mul_f32 v[216:217], v[164:165], v[216:217]
	v_bfe_u32 v210, v209, 16, 1
	v_bfe_u32 v218, v215, 16, 1
	v_bfe_u32 v211, v208, 16, 1
	v_bfe_u32 v219, v214, 16, 1
	v_add3_u32 v215, v215, v218, s55
	v_add3_u32 v209, v209, v210, s55
	v_bfe_u32 v210, v212, 16, 1
	v_bfe_u32 v218, v216, 16, 1
	v_add3_u32 v214, v214, v219, s55
	v_add3_u32 v208, v208, v211, s55
	v_bfe_u32 v211, v213, 16, 1
	v_bfe_u32 v219, v217, 16, 1
	v_add3_u32 v216, v216, v218, s55
	v_add3_u32 v210, v212, v210, s55
	v_add3_u32 v217, v217, v219, s55
	v_add3_u32 v211, v213, v211, s55
	v_lshrrev_b32_e32 v212, 16, v210
	v_lshrrev_b32_e32 v210, 16, v216
	v_lshrrev_b32_e32 v213, 16, v211
	v_lshrrev_b32_e32 v211, 16, v217
	v_and_or_b32 v210, v208, s56, v210
	v_and_or_b32 v208, v214, s56, v212
	v_or_b32_e32 v212, v206, v196
	v_and_or_b32 v211, v209, s56, v211
	v_and_or_b32 v209, v215, s56, v213
	v_and_or_b32 v213, v212, s67, v207
	v_cndmask_b32_e64 v212, v213, v212, s[4:5]
	v_add_u32_e32 v212, v212, v204
	v_ashrrev_i32_e32 v215, 31, v212
	v_mad_u64_u32 v[212:213], s[0:1], v212, v202, 0
	v_mov_b32_e32 v214, v213
	v_mad_u64_u32 v[214:215], s[0:1], v215, v202, v[214:215]
	v_mov_b32_e32 v213, v214
	v_lshl_add_u64 v[212:213], v[212:213], 1, v[160:161]
	v_lshl_add_u64 v[212:213], v[212:213], 0, v[170:171]
	v_lshl_add_u64 v[212:213], v[212:213], 0, v[162:163]
	global_store_dwordx4 v[212:213], v[208:211], off sc1 nt
	ds_read2st64_b32 v[208:209], v199 offset1:1
	ds_read2st64_b32 v[210:211], v199 offset0:2 offset1:3
	ds_read2st64_b32 v[212:213], v199 offset0:4 offset1:5
	ds_read2st64_b32 v[214:215], v199 offset0:6 offset1:7
	v_or_b32_e32 v206, v206, v198
	v_and_or_b32 v207, v206, s54, v207
	v_cndmask_b32_e64 v206, v207, v206, s[4:5]
	v_add_u32_e32 v216, v206, v204
	s_waitcnt lgkmcnt(3)
	v_mov_b32_e32 v206, v209
	s_waitcnt lgkmcnt(2)
	v_mov_b32_e32 v207, v211
	v_pk_mul_f32 v[166:167], v[166:167], v[206:207]
	s_waitcnt lgkmcnt(1)
	v_mov_b32_e32 v206, v213
	s_waitcnt lgkmcnt(0)
	v_mov_b32_e32 v207, v215
	v_mov_b32_e32 v209, v210
	v_pk_mul_f32 v[168:169], v[168:169], v[206:207]
	v_mov_b32_e32 v213, v214
	v_pk_mul_f32 v[4:5], v[4:5], v[208:209]
	v_pk_mul_f32 v[164:165], v[164:165], v[212:213]
	v_bfe_u32 v206, v169, 16, 1
	v_bfe_u32 v207, v168, 16, 1
	v_bfe_u32 v208, v167, 16, 1
	v_bfe_u32 v209, v166, 16, 1
	v_add3_u32 v209, v166, v209, s55
	v_add3_u32 v208, v167, v208, s55
	v_add3_u32 v166, v168, v207, s55
	v_add3_u32 v167, v169, v206, s55
	v_bfe_u32 v168, v4, 16, 1
	v_bfe_u32 v169, v5, 16, 1
	v_bfe_u32 v206, v164, 16, 1
	v_bfe_u32 v207, v165, 16, 1
	v_add3_u32 v165, v165, v207, s55
	v_add3_u32 v164, v164, v206, s55
	v_add3_u32 v5, v5, v169, s55
	v_add3_u32 v4, v4, v168, s55
	v_lshrrev_b32_e32 v4, 16, v4
	v_lshrrev_b32_e32 v5, 16, v5
	v_lshrrev_b32_e32 v164, 16, v164
	v_lshrrev_b32_e32 v165, 16, v165
	v_and_or_b32 v167, v167, s56, v165
	v_and_or_b32 v166, v166, s56, v164
	v_and_or_b32 v165, v208, s56, v5
	v_and_or_b32 v164, v209, s56, v4
	v_mad_u64_u32 v[4:5], s[0:1], v216, v202, 0
	v_ashrrev_i32_e32 v169, 31, v216
	v_mov_b32_e32 v168, v5
	v_mad_u64_u32 v[168:169], s[0:1], v169, v202, v[168:169]
	v_mov_b32_e32 v5, v168
	v_lshl_add_u64 v[4:5], v[4:5], 1, v[160:161]
	v_lshl_add_u64 v[4:5], v[4:5], 0, v[170:171]
	v_lshl_add_u64 v[4:5], v[4:5], 0, v[162:163]
	global_store_dwordx4 v[4:5], v[164:167], off sc1 nt
	s_waitcnt lgkmcnt(0)
	s_and_b64 s[0:1], vcc, exec

; #define LAS __attribute__((address_space(3)))
; __device__ __forceinline__ unsigned pk2(float lo, float hi) { return f2bf(lo) | (f2bf(hi) << 16); }
; __device__ __forceinline__ void cv_process(const CvDesc& d, int lane, const f32x4 (&v)[16], const f32x4& g0, const f32x4& g1, LAS float* scr) {
;     ...
;     for (int j = 0; j < 8; ++j) { const int n = (lane >> 3) + 8 * j; const LAS float* s = scr + (8 * c) * 64 + (n ^ (8 * c));
;         u32x4 o; o.x = pk2(s[0 * 64] * g0[0], s[1 * 64] * g0[1]); o.y = pk2(s[2 * 64] * g0[2], s[3 * 64] * g0[3]); o.z = pk2(s[4 * 64] * g1[0], s[5 * 64] * g1[1]); o.w = pk2(s[6 * 64] * g1[2], s[7 * 64] * g1[3]);
;         const int ng = n0 + n, drow = d.mode ? (((ng >> 7) << 8) + (ng & 127) + d.off) : (d.off + ng);
;         *(u32x4*)(d.dst + (size_t)drow * d.K + k0 + 8 * c) = o; }
.Lcv_ladA_done:
	s_waitcnt lgkmcnt(0)
	v_ashrrev_i32_e32 v162, 31, v174
	v_mul_f32_e32 v5, 0x4f7ffffe, v5
	v_cvt_u32_f32_e32 v5, v5
	v_mul_lo_u32 v164, v164, v5
	v_mul_hi_u32 v164, v5, v164
	v_add_u32_e32 v5, v5, v164
	v_mul_hi_u32 v5, v163, v5
	v_mul_lo_u32 v164, v5, v4
	v_sub_u32_e32 v163, v163, v164
	v_add_u32_e32 v165, 1, v5
	v_cmp_ge_u32_e64 s[4:5], v163, v4
	v_sub_u32_e32 v164, v163, v4
	s_nop 0
	v_cndmask_b32_e64 v5, v5, v165, s[4:5]
	v_cndmask_b32_e64 v163, v163, v164, s[4:5]
	v_add_u32_e32 v164, 1, v5
	v_cmp_ge_u32_e64 s[4:5], v163, v4
	s_nop 1
	v_cndmask_b32_e64 v5, v5, v164, s[4:5]
	v_xor_b32_e32 v5, v5, v162
	ds_read2st64_b32 v[164:165], v185 offset1:1
	ds_read2st64_b32 v[168:169], v185 offset0:2 offset1:3
	v_sub_u32_e32 v5, v5, v162
	v_mul_lo_u32 v4, v5, v4
	ds_read2st64_b32 v[170:171], v185 offset0:4 offset1:5
	ds_read2st64_b32 v[210:211], v185 offset0:6 offset1:7
	v_sub_u32_e32 v4, v174, v4
	v_lshlrev_b32_e32 v207, 6, v4
	v_lshlrev_b32_e32 v4, 7, v4
	v_lshlrev_b32_e32 v162, 6, v5
	v_and_b32_e32 v208, 0xffffff00, v4
	v_mov_b32_e32 v4, v70
	v_mov_b32_e32 v5, v72
	s_waitcnt lgkmcnt(3)
	v_mov_b32_e32 v166, v164
	s_waitcnt lgkmcnt(2)
	v_mov_b32_e32 v167, v168
	v_pk_mul_f32 v[212:213], v[4:5], v[166:167]
	v_mov_b32_e32 v166, v71
	v_mov_b32_e32 v167, v73
	v_mov_b32_e32 v168, v165
	v_pk_mul_f32 v[214:215], v[166:167], v[168:169]
	v_mov_b32_e32 v164, v74
	v_mov_b32_e32 v165, v76
	s_waitcnt lgkmcnt(1)
	v_mov_b32_e32 v168, v170
	s_waitcnt lgkmcnt(0)
	v_mov_b32_e32 v169, v210
	v_pk_mul_f32 v[216:217], v[164:165], v[168:169]
	v_mov_b32_e32 v168, v75
	v_mov_b32_e32 v169, v77
	v_mov_b32_e32 v210, v171
	v_pk_mul_f32 v[170:171], v[168:169], v[210:211]
	v_bfe_u32 v211, v215, 16, 1
	v_bfe_u32 v209, v171, 16, 1
	v_bfe_u32 v218, v214, 16, 1
	v_add3_u32 v211, v215, v211, s55
	v_bfe_u32 v215, v216, 16, 1
	v_bfe_u32 v210, v170, 16, 1
	v_add3_u32 v214, v214, v218, s55
	v_add3_u32 v171, v171, v209, s55
	v_bfe_u32 v209, v212, 16, 1
	v_bfe_u32 v218, v217, 16, 1
	v_add3_u32 v215, v216, v215, s55
	v_add3_u32 v170, v170, v210, s55
	v_bfe_u32 v210, v213, 16, 1
	v_add3_u32 v217, v217, v218, s55
	v_add3_u32 v209, v212, v209, s55
	v_lshrrev_b32_e32 v212, 16, v215
	v_add3_u32 v210, v213, v210, s55
	v_lshrrev_b32_e32 v213, 16, v217
	v_and_or_b32 v212, v170, s56, v212
	v_or_b32_e32 v170, v207, v184
	v_and_or_b32 v213, v171, s56, v213
	v_and_or_b32 v171, v170, s57, v208
	v_cmp_eq_u32_e64 s[4:5], 0, v172
	v_lshrrev_b32_e32 v209, 16, v209
	v_lshrrev_b32_e32 v210, 16, v210
	v_cndmask_b32_e64 v170, v171, v170, s[4:5]
	v_add_u32_e32 v170, v170, v173
	v_and_or_b32 v211, v211, s56, v210
	v_and_or_b32 v210, v214, s56, v209
	v_ashrrev_i32_e32 v209, 31, v170
	v_mad_u64_u32 v[170:171], s[0:1], v170, v153, 0
	v_mov_b32_e32 v214, v171
	v_mad_u64_u32 v[214:215], s[0:1], v209, v153, v[214:215]
	v_ashrrev_i32_e32 v163, 31, v162
	v_mov_b32_e32 v171, v214
	v_lshl_add_u64 v[214:215], v[170:171], 1, v[154:155]
	v_lshlrev_b64 v[170:171], 1, v[162:163]
	v_lshl_add_u64 v[214:215], v[214:215], 0, v[170:171]
	v_lshlrev_b64 v[162:163], 1, v[158:159]
	v_lshl_add_u64 v[214:215], v[214:215], 0, v[162:163]
	ds_read2st64_b32 v[216:217], v187 offset1:1
	ds_read2st64_b32 v[218:219], v187 offset0:2 offset1:3
	global_store_dwordx4 v[214:215], v[210:213], off sc1 nt
	ds_read2st64_b32 v[210:211], v187 offset0:4 offset1:5
	ds_read2st64_b32 v[212:213], v187 offset0:6 offset1:7
	s_waitcnt lgkmcnt(3)
	v_mov_b32_e32 v214, v216
	s_waitcnt lgkmcnt(2)
	v_mov_b32_e32 v215, v218
	v_mov_b32_e32 v218, v217
	v_pk_mul_f32 v[216:217], v[166:167], v[218:219]
	s_waitcnt lgkmcnt(0)
	v_mov_b32_e32 v219, v212
	v_mov_b32_e32 v212, v211
	v_mov_b32_e32 v218, v210
	v_pk_mul_f32 v[210:211], v[168:169], v[212:213]
	v_pk_mul_f32 v[214:215], v[4:5], v[214:215]
	v_pk_mul_f32 v[218:219], v[164:165], v[218:219]
	v_bfe_u32 v209, v211, 16, 1
	v_bfe_u32 v212, v210, 16, 1
	v_bfe_u32 v213, v217, 16, 1
	v_bfe_u32 v220, v216, 16, 1
	v_add3_u32 v216, v216, v220, s55
	v_add3_u32 v217, v217, v213, s55
	v_add3_u32 v210, v210, v212, s55
	v_add3_u32 v209, v211, v209, s55
	v_bfe_u32 v211, v214, 16, 1
	v_bfe_u32 v212, v215, 16, 1
	v_bfe_u32 v213, v218, 16, 1
	v_bfe_u32 v220, v219, 16, 1
	v_add3_u32 v219, v219, v220, s55
	v_add3_u32 v213, v218, v213, s55
	v_add3_u32 v212, v215, v212, s55
	v_add3_u32 v211, v214, v211, s55
	v_lshrrev_b32_e32 v214, 16, v211
	v_lshrrev_b32_e32 v211, 16, v212
	v_lshrrev_b32_e32 v212, 16, v213
	v_lshrrev_b32_e32 v213, 16, v219
	v_and_or_b32 v213, v209, s56, v213
	v_or_b32_e32 v209, v207, v186
	v_and_or_b32 v212, v210, s56, v212
	v_and_or_b32 v210, v216, s56, v214
	v_and_or_b32 v214, v209, s62, v208
	v_cndmask_b32_e64 v209, v214, v209, s[4:5]
	v_add_u32_e32 v209, v209, v173
	v_mad_u64_u32 v[214:215], s[0:1], v209, v153, 0
	v_and_or_b32 v211, v217, s56, v211
	v_ashrrev_i32_e32 v217, 31, v209
	v_mov_b32_e32 v216, v215
	v_mad_u64_u32 v[216:217], s[0:1], v217, v153, v[216:217]
	v_mov_b32_e32 v215, v216
	v_lshl_add_u64 v[214:215], v[214:215], 1, v[154:155]
	v_lshl_add_u64 v[214:215], v[214:215], 0, v[170:171]
	v_lshl_add_u64 v[214:215], v[214:215], 0, v[162:163]
	ds_read2st64_b32 v[216:217], v189 offset1:1
	ds_read2st64_b32 v[218:219], v189 offset0:2 offset1:3
	global_store_dwordx4 v[214:215], v[210:213], off sc1 nt
	ds_read2st64_b32 v[210:211], v189 offset0:4 offset1:5
	ds_read2st64_b32 v[212:213], v189 offset0:6 offset1:7
	s_waitcnt lgkmcnt(3)
	v_mov_b32_e32 v214, v216
	s_waitcnt lgkmcnt(2)
	v_mov_b32_e32 v215, v218
	v_mov_b32_e32 v218, v217
	v_pk_mul_f32 v[216:217], v[166:167], v[218:219]
	s_waitcnt lgkmcnt(0)
; #define LAS __attribute__((address_space(3)))
; __device__ __forceinline__ unsigned pk2(float lo, float hi) { return f2bf(lo) | (f2bf(hi) << 16); }
; __device__ __forceinline__ void cv_process(const CvDesc& d, int lane, const f32x4 (&v)[16], const f32x4& g0, const f32x4& g1, LAS float* scr) {
;     ...
;     for (int j = 0; j < 8; ++j) { const int n = (lane >> 3) + 8 * j; const LAS float* s = scr + (8 * c) * 64 + (n ^ (8 * c));
;         u32x4 o; o.x = pk2(s[0 * 64] * g0[0], s[1 * 64] * g0[1]); o.y = pk2(s[2 * 64] * g0[2], s[3 * 64] * g0[3]); o.z = pk2(s[4 * 64] * g1[0], s[5 * 64] * g1[1]); o.w = pk2(s[6 * 64] * g1[2], s[7 * 64] * g1[3]);
;         const int ng = n0 + n, drow = d.mode ? (((ng >> 7) << 8) + (ng & 127) + d.off) : (d.off + ng);
;         *(u32x4*)(d.dst + (size_t)drow * d.K + k0 + 8 * c) = o; }
	v_mov_b32_e32 v219, v212
	v_mov_b32_e32 v212, v211
	v_mov_b32_e32 v218, v210
	v_pk_mul_f32 v[210:211], v[168:169], v[212:213]
	v_pk_mul_f32 v[214:215], v[4:5], v[214:215]
	v_pk_mul_f32 v[218:219], v[164:165], v[218:219]
	v_bfe_u32 v209, v211, 16, 1
	v_bfe_u32 v212, v210, 16, 1
	v_bfe_u32 v213, v217, 16, 1
	v_bfe_u32 v220, v216, 16, 1
	v_add3_u32 v216, v216, v220, s55
	v_add3_u32 v217, v217, v213, s55
	v_add3_u32 v210, v210, v212, s55
	v_add3_u32 v209, v211, v209, s55
	v_bfe_u32 v211, v214, 16, 1
	v_bfe_u32 v212, v215, 16, 1
	v_bfe_u32 v213, v218, 16, 1
	v_bfe_u32 v220, v219, 16, 1
	v_add3_u32 v219, v219, v220, s55
	v_add3_u32 v213, v218, v213, s55
	v_add3_u32 v212, v215, v212, s55
	v_add3_u32 v211, v214, v211, s55
	v_lshrrev_b32_e32 v214, 16, v211
	v_lshrrev_b32_e32 v211, 16, v212
	v_lshrrev_b32_e32 v212, 16, v213
	v_lshrrev_b32_e32 v213, 16, v219
	v_and_or_b32 v213, v209, s56, v213
	v_or_b32_e32 v209, v207, v188
	v_and_or_b32 v212, v210, s56, v212
	v_and_or_b32 v210, v216, s56, v214
	v_and_or_b32 v214, v209, s63, v208
	v_cndmask_b32_e64 v209, v214, v209, s[4:5]
	v_add_u32_e32 v209, v209, v173
	v_mad_u64_u32 v[214:215], s[0:1], v209, v153, 0
	v_and_or_b32 v211, v217, s56, v211
	v_ashrrev_i32_e32 v217, 31, v209
	v_mov_b32_e32 v216, v215
	v_mad_u64_u32 v[216:217], s[0:1], v217, v153, v[216:217]
	v_mov_b32_e32 v215, v216
	v_lshl_add_u64 v[214:215], v[214:215], 1, v[154:155]
	v_lshl_add_u64 v[214:215], v[214:215], 0, v[170:171]
	v_lshl_add_u64 v[214:215], v[214:215], 0, v[162:163]
	ds_read2st64_b32 v[216:217], v191 offset1:1
	ds_read2st64_b32 v[218:219], v191 offset0:2 offset1:3
	global_store_dwordx4 v[214:215], v[210:213], off sc1 nt
	ds_read2st64_b32 v[210:211], v191 offset0:4 offset1:5
	ds_read2st64_b32 v[212:213], v191 offset0:6 offset1:7
	s_waitcnt lgkmcnt(3)
	v_mov_b32_e32 v214, v216
	s_waitcnt lgkmcnt(2)
	v_mov_b32_e32 v215, v218
	v_mov_b32_e32 v218, v217
	v_pk_mul_f32 v[216:217], v[166:167], v[218:219]
	s_waitcnt lgkmcnt(0)
	v_mov_b32_e32 v219, v212
	v_mov_b32_e32 v212, v211
	v_mov_b32_e32 v218, v210
	v_pk_mul_f32 v[210:211], v[168:169], v[212:213]
	v_pk_mul_f32 v[214:215], v[4:5], v[214:215]
	v_pk_mul_f32 v[218:219], v[164:165], v[218:219]
	v_bfe_u32 v209, v211, 16, 1
	v_bfe_u32 v212, v210, 16, 1
	v_bfe_u32 v213, v217, 16, 1
	v_bfe_u32 v220, v216, 16, 1
	v_add3_u32 v216, v216, v220, s55
	v_add3_u32 v217, v217, v213, s55
	v_add3_u32 v210, v210, v212, s55
	v_add3_u32 v209, v211, v209, s55
	v_bfe_u32 v211, v214, 16, 1
	v_bfe_u32 v212, v215, 16, 1
	v_bfe_u32 v213, v218, 16, 1
	v_bfe_u32 v220, v219, 16, 1
	v_add3_u32 v219, v219, v220, s55
	v_add3_u32 v213, v218, v213, s55
	v_add3_u32 v212, v215, v212, s55
	v_add3_u32 v211, v214, v211, s55
	v_lshrrev_b32_e32 v214, 16, v211
	v_lshrrev_b32_e32 v211, 16, v212
	v_lshrrev_b32_e32 v212, 16, v213
	v_lshrrev_b32_e32 v213, 16, v219
	v_and_or_b32 v213, v209, s56, v213
	v_or_b32_e32 v209, v207, v190
	v_and_or_b32 v212, v210, s56, v212
	v_and_or_b32 v210, v216, s56, v214
	v_and_or_b32 v214, v209, s64, v208
	v_cndmask_b32_e64 v209, v214, v209, s[4:5]
	v_add_u32_e32 v209, v209, v173
	v_mad_u64_u32 v[214:215], s[0:1], v209, v153, 0
	v_and_or_b32 v211, v217, s56, v211
	v_ashrrev_i32_e32 v217, 31, v209
	v_mov_b32_e32 v216, v215
	v_mad_u64_u32 v[216:217], s[0:1], v217, v153, v[216:217]
	v_mov_b32_e32 v215, v216
	v_lshl_add_u64 v[214:215], v[214:215], 1, v[154:155]
	v_lshl_add_u64 v[214:215], v[214:215], 0, v[170:171]
	v_lshl_add_u64 v[214:215], v[214:215], 0, v[162:163]
	ds_read2st64_b32 v[216:217], v193 offset1:1
	ds_read2st64_b32 v[218:219], v193 offset0:2 offset1:3
	global_store_dwordx4 v[214:215], v[210:213], off sc1 nt
	ds_read2st64_b32 v[210:211], v193 offset0:4 offset1:5
	ds_read2st64_b32 v[212:213], v193 offset0:6 offset1:7
	s_waitcnt lgkmcnt(3)
	v_mov_b32_e32 v214, v216
	s_waitcnt lgkmcnt(2)
	v_mov_b32_e32 v215, v218
	v_mov_b32_e32 v218, v217
	v_pk_mul_f32 v[216:217], v[166:167], v[218:219]
	s_waitcnt lgkmcnt(0)
	v_mov_b32_e32 v219, v212
	v_mov_b32_e32 v212, v211
	v_mov_b32_e32 v218, v210
	v_pk_mul_f32 v[210:211], v[168:169], v[212:213]
	v_pk_mul_f32 v[214:215], v[4:5], v[214:215]
	v_pk_mul_f32 v[218:219], v[164:165], v[218:219]
	v_bfe_u32 v209, v211, 16, 1
	v_bfe_u32 v212, v210, 16, 1
	v_bfe_u32 v213, v217, 16, 1
	v_bfe_u32 v220, v216, 16, 1
	v_add3_u32 v216, v216, v220, s55
	v_add3_u32 v217, v217, v213, s55
	v_add3_u32 v210, v210, v212, s55
	v_add3_u32 v209, v211, v209, s55
	v_bfe_u32 v211, v214, 16, 1
	v_bfe_u32 v212, v215, 16, 1
	v_bfe_u32 v213, v218, 16, 1
	v_bfe_u32 v220, v219, 16, 1
	v_add3_u32 v219, v219, v220, s55
	v_add3_u32 v213, v218, v213, s55
	v_add3_u32 v212, v215, v212, s55
	v_add3_u32 v211, v214, v211, s55
	v_lshrrev_b32_e32 v214, 16, v211
	v_lshrrev_b32_e32 v211, 16, v212
	v_lshrrev_b32_e32 v212, 16, v213
	v_lshrrev_b32_e32 v213, 16, v219
	v_and_or_b32 v213, v209, s56, v213
	v_or_b32_e32 v209, v207, v192
	v_and_or_b32 v212, v210, s56, v212
	v_and_or_b32 v210, v216, s56, v214
	v_and_or_b32 v214, v209, s65, v208
	v_cndmask_b32_e64 v209, v214, v209, s[4:5]
	v_add_u32_e32 v209, v209, v173
	v_mad_u64_u32 v[214:215], s[0:1], v209, v153, 0
	v_and_or_b32 v211, v217, s56, v211
	v_ashrrev_i32_e32 v217, 31, v209
	v_mov_b32_e32 v216, v215
	v_mad_u64_u32 v[216:217], s[0:1], v217, v153, v[216:217]
	v_mov_b32_e32 v215, v216
	v_lshl_add_u64 v[214:215], v[214:215], 1, v[154:155]
	v_lshl_add_u64 v[214:215], v[214:215], 0, v[170:171]
	v_lshl_add_u64 v[214:215], v[214:215], 0, v[162:163]
	ds_read2st64_b32 v[216:217], v195 offset1:1
	ds_read2st64_b32 v[218:219], v195 offset0:2 offset1:3
	global_store_dwordx4 v[214:215], v[210:213], off sc1 nt
	ds_read2st64_b32 v[210:211], v195 offset0:4 offset1:5
	ds_read2st64_b32 v[212:213], v195 offset0:6 offset1:7
	s_waitcnt lgkmcnt(3)
; #define LAS __attribute__((address_space(3)))
; __device__ __forceinline__ unsigned pk2(float lo, float hi) { return f2bf(lo) | (f2bf(hi) << 16); }
; __device__ __forceinline__ void cv_process(const CvDesc& d, int lane, const f32x4 (&v)[16], const f32x4& g0, const f32x4& g1, LAS float* scr) {
;     ...
;     for (int j = 0; j < 8; ++j) { const int n = (lane >> 3) + 8 * j; const LAS float* s = scr + (8 * c) * 64 + (n ^ (8 * c));
;         u32x4 o; o.x = pk2(s[0 * 64] * g0[0], s[1 * 64] * g0[1]); o.y = pk2(s[2 * 64] * g0[2], s[3 * 64] * g0[3]); o.z = pk2(s[4 * 64] * g1[0], s[5 * 64] * g1[1]); o.w = pk2(s[6 * 64] * g1[2], s[7 * 64] * g1[3]);
;         const int ng = n0 + n, drow = d.mode ? (((ng >> 7) << 8) + (ng & 127) + d.off) : (d.off + ng);
;         *(u32x4*)(d.dst + (size_t)drow * d.K + k0 + 8 * c) = o; }
	v_mov_b32_e32 v214, v216
	s_waitcnt lgkmcnt(2)
	v_mov_b32_e32 v215, v218
	v_mov_b32_e32 v218, v217
	v_pk_mul_f32 v[216:217], v[166:167], v[218:219]
	s_waitcnt lgkmcnt(0)
	v_mov_b32_e32 v219, v212
	v_mov_b32_e32 v212, v211
	v_mov_b32_e32 v218, v210
	v_pk_mul_f32 v[210:211], v[168:169], v[212:213]
	v_pk_mul_f32 v[214:215], v[4:5], v[214:215]
	v_pk_mul_f32 v[218:219], v[164:165], v[218:219]
	v_bfe_u32 v209, v211, 16, 1
	v_bfe_u32 v212, v210, 16, 1
	v_bfe_u32 v213, v217, 16, 1
	v_bfe_u32 v220, v216, 16, 1
	v_add3_u32 v216, v216, v220, s55
	v_add3_u32 v217, v217, v213, s55
	v_add3_u32 v210, v210, v212, s55
	v_add3_u32 v209, v211, v209, s55
	v_bfe_u32 v211, v214, 16, 1
	v_bfe_u32 v212, v215, 16, 1
	v_bfe_u32 v213, v218, 16, 1
	v_bfe_u32 v220, v219, 16, 1
	v_add3_u32 v219, v219, v220, s55
	v_add3_u32 v213, v218, v213, s55
	v_add3_u32 v212, v215, v212, s55
	v_add3_u32 v211, v214, v211, s55
	v_lshrrev_b32_e32 v214, 16, v211
	v_lshrrev_b32_e32 v211, 16, v212
	v_lshrrev_b32_e32 v212, 16, v213
	v_lshrrev_b32_e32 v213, 16, v219
	v_and_or_b32 v213, v209, s56, v213
	v_or_b32_e32 v209, v207, v194
	v_and_or_b32 v212, v210, s56, v212
	v_and_or_b32 v210, v216, s56, v214
	v_and_or_b32 v214, v209, s66, v208
	v_cndmask_b32_e64 v209, v214, v209, s[4:5]
	v_add_u32_e32 v209, v209, v173
	v_mad_u64_u32 v[214:215], s[0:1], v209, v153, 0
	v_and_or_b32 v211, v217, s56, v211
	v_ashrrev_i32_e32 v217, 31, v209
	v_mov_b32_e32 v216, v215
	v_mad_u64_u32 v[216:217], s[0:1], v217, v153, v[216:217]
	v_mov_b32_e32 v215, v216
	v_lshl_add_u64 v[214:215], v[214:215], 1, v[154:155]
	v_lshl_add_u64 v[214:215], v[214:215], 0, v[170:171]
	v_lshl_add_u64 v[214:215], v[214:215], 0, v[162:163]
	ds_read2st64_b32 v[216:217], v197 offset1:1
	ds_read2st64_b32 v[218:219], v197 offset0:2 offset1:3
	global_store_dwordx4 v[214:215], v[210:213], off sc1 nt
	ds_read2st64_b32 v[210:211], v197 offset0:4 offset1:5
	ds_read2st64_b32 v[212:213], v197 offset0:6 offset1:7
	s_waitcnt lgkmcnt(3)
	v_mov_b32_e32 v214, v216
	s_waitcnt lgkmcnt(2)
	v_mov_b32_e32 v215, v218
	v_mov_b32_e32 v218, v217
	v_pk_mul_f32 v[216:217], v[166:167], v[218:219]
	s_waitcnt lgkmcnt(0)
	v_mov_b32_e32 v219, v212
	v_mov_b32_e32 v212, v211
	v_mov_b32_e32 v218, v210
	v_pk_mul_f32 v[210:211], v[168:169], v[212:213]
	v_pk_mul_f32 v[214:215], v[4:5], v[214:215]
	v_pk_mul_f32 v[218:219], v[164:165], v[218:219]
	v_bfe_u32 v209, v211, 16, 1
	v_bfe_u32 v212, v210, 16, 1
	v_bfe_u32 v213, v217, 16, 1
	v_bfe_u32 v220, v216, 16, 1
	v_add3_u32 v216, v216, v220, s55
	v_add3_u32 v217, v217, v213, s55
	v_add3_u32 v210, v210, v212, s55
	v_add3_u32 v209, v211, v209, s55
	v_bfe_u32 v211, v214, 16, 1
	v_bfe_u32 v212, v215, 16, 1
	v_bfe_u32 v213, v218, 16, 1
	v_bfe_u32 v220, v219, 16, 1
	v_add3_u32 v219, v219, v220, s55
	v_add3_u32 v213, v218, v213, s55
	v_add3_u32 v212, v215, v212, s55
	v_add3_u32 v211, v214, v211, s55
	v_lshrrev_b32_e32 v214, 16, v211
	v_lshrrev_b32_e32 v211, 16, v212
	v_lshrrev_b32_e32 v212, 16, v213
	v_lshrrev_b32_e32 v213, 16, v219
	v_and_or_b32 v213, v209, s56, v213
	v_or_b32_e32 v209, v207, v196
	v_and_or_b32 v212, v210, s56, v212
	v_and_or_b32 v210, v216, s56, v214
	v_and_or_b32 v214, v209, s67, v208
	v_cndmask_b32_e64 v209, v214, v209, s[4:5]
	v_add_u32_e32 v209, v209, v173
	v_mad_u64_u32 v[214:215], s[0:1], v209, v153, 0
	v_and_or_b32 v211, v217, s56, v211
	v_ashrrev_i32_e32 v217, 31, v209
	v_mov_b32_e32 v216, v215
	v_mad_u64_u32 v[216:217], s[0:1], v217, v153, v[216:217]
	v_mov_b32_e32 v215, v216
	v_lshl_add_u64 v[214:215], v[214:215], 1, v[154:155]
	v_lshl_add_u64 v[214:215], v[214:215], 0, v[170:171]
	v_lshl_add_u64 v[214:215], v[214:215], 0, v[162:163]
	global_store_dwordx4 v[214:215], v[210:213], off sc1 nt
	ds_read2st64_b32 v[210:211], v199 offset1:1
	ds_read2st64_b32 v[212:213], v199 offset0:2 offset1:3
	ds_read2st64_b32 v[214:215], v199 offset0:4 offset1:5
	ds_read2st64_b32 v[216:217], v199 offset0:6 offset1:7
	v_or_b32_e32 v207, v207, v198
	v_and_or_b32 v208, v207, s54, v208
	v_cndmask_b32_e64 v207, v208, v207, s[4:5]
	s_waitcnt lgkmcnt(3)
	v_mov_b32_e32 v208, v211
	s_waitcnt lgkmcnt(2)
	v_mov_b32_e32 v209, v213
	v_pk_mul_f32 v[166:167], v[166:167], v[208:209]
	s_waitcnt lgkmcnt(1)
	v_mov_b32_e32 v208, v215
	s_waitcnt lgkmcnt(0)
	v_mov_b32_e32 v209, v217
	v_mov_b32_e32 v211, v212
	v_pk_mul_f32 v[168:169], v[168:169], v[208:209]
	v_mov_b32_e32 v215, v216
	v_pk_mul_f32 v[4:5], v[4:5], v[210:211]
	v_pk_mul_f32 v[164:165], v[164:165], v[214:215]
	v_bfe_u32 v208, v169, 16, 1
	v_bfe_u32 v209, v168, 16, 1
	v_bfe_u32 v210, v167, 16, 1
	v_bfe_u32 v211, v166, 16, 1
	v_add3_u32 v211, v166, v211, s55
	v_add3_u32 v210, v167, v210, s55
	v_add3_u32 v166, v168, v209, s55
	v_add3_u32 v167, v169, v208, s55
	v_bfe_u32 v168, v4, 16, 1
	v_bfe_u32 v169, v5, 16, 1
	v_bfe_u32 v208, v164, 16, 1
	v_bfe_u32 v209, v165, 16, 1
	v_add3_u32 v165, v165, v209, s55
	v_add3_u32 v164, v164, v208, s55
	v_add3_u32 v5, v5, v169, s55
	v_add3_u32 v4, v4, v168, s55
	v_add_u32_e32 v207, v207, v173
	v_lshrrev_b32_e32 v4, 16, v4
	v_lshrrev_b32_e32 v5, 16, v5
	v_lshrrev_b32_e32 v164, 16, v164
	v_lshrrev_b32_e32 v165, 16, v165
	v_and_or_b32 v167, v167, s56, v165
	v_and_or_b32 v166, v166, s56, v164
	v_and_or_b32 v165, v210, s56, v5
	v_and_or_b32 v164, v211, s56, v4
	v_mad_u64_u32 v[4:5], s[0:1], v207, v153, 0
	v_ashrrev_i32_e32 v169, 31, v207
	v_mov_b32_e32 v168, v5
	v_mad_u64_u32 v[168:169], s[0:1], v169, v153, v[168:169]
	v_mov_b32_e32 v5, v168
	v_lshl_add_u64 v[4:5], v[4:5], 1, v[154:155]
	v_lshl_add_u64 v[4:5], v[4:5], 0, v[170:171]
	v_lshl_add_u64 v[4:5], v[4:5], 0, v[162:163]
	global_store_dwordx4 v[4:5], v[164:167], off sc1 nt
	s_waitcnt lgkmcnt(0)
	s_mov_b64 s[0:1], 0
	s_and_saveexec_b64 s[36:37], vcc
	s_cbranch_execz .LBB0_142
; #define PLE_JOBS(L) \
;     JOB(CV_DD, a.in[12] + (size_t)(L) * D * D, D, D, ws + WS_WG + (size_t)(L) * SZ_WG, a.in[11] + (L) * D, 0, 0) \
;     JOB(CV_PJ, a.in[13] + (size_t)(L) * PLE * D, PLE, D, ws + WS_WP + (size_t)(L) * SZ_WP, nullptr, 0, 0)
; __device__ __forceinline__ CvDesc cv_decode(const Args& a, int it) {
;     ...
;     int r = it; CvDesc d; d.src = nullptr; d.dst = nullptr; d.gain = nullptr; d.K = 64; d.N = 64; d.mode = 0; d.off = 0; d.r = 0; bool hit = false;
;     ...
;     FFN_JOBS(0, 0, 3, 4, 5, 2) FFN_JOBS(1, 0, 8, 9, 10, 7) PLE_JOBS(0)
	s_mov_b32 s99, 0
	v_add_u32_e32 v168, s42, v206
	v_cmp_gt_i32_e32 vcc, s3, v168
	s_and_saveexec_b64 s[38:39], vcc
	s_cbranch_execz .LBB0_141
	s_mov_b32 s99, 1
	v_cmp_lt_i32_e64 s[4:5], s43, v168
	v_mov_b32_e32 v172, 1
	v_mov_b32_e32 v153, 0x800
	v_mov_b32_e32 v151, 0x1600
	v_mov_b64_e32 v[164:165], s[8:9]
	v_mov_b64_e32 v[154:155], s[44:45]
	v_mov_b64_e32 v[4:5], s[10:11]
	v_mov_b32_e32 v174, v168
	v_mov_b32_e32 v3, v168
	s_and_saveexec_b64 s[0:1], s[4:5]
	v_add_u32_e32 v3, 0xfffff500, v168
	v_mov_b32_e32 v172, 0
	v_mov_b64_e32 v[164:165], 0
	v_mov_b32_e32 v151, 64
	v_mov_b32_e32 v153, 64
	v_mov_b64_e32 v[154:155], 0
	v_mov_b64_e32 v[4:5], 0
	v_mov_b32_e32 v174, 0
	s_or_b64 exec, exec, s[0:1]
	s_mov_b64 s[46:47], -1
	v_mov_b32_e32 v173, 0
	s_mov_b64 s[50:51], -1
	s_and_saveexec_b64 s[0:1], s[4:5]
	s_cbranch_execz .LBB0_239
	v_cmp_lt_i32_e64 s[4:5], s43, v3
	v_mov_b32_e32 v15, 0x1600
	v_mov_b32_e32 v14, 0x800
	v_mov_b32_e32 v12, 1
	v_mov_b32_e32 v173, 0x80
	v_mov_b64_e32 v[6:7], s[12:13]
	v_mov_b64_e32 v[8:9], s[44:45]
	v_mov_b64_e32 v[10:11], s[8:9]
	v_mov_b32_e32 v13, v3
	s_and_saveexec_b64 s[52:53], s[4:5]
	s_cbranch_execz .LBB0_238
	v_add_u32_e32 v3, 0xfffff500, v3
	v_mov_b32_e32 v173, 0
	s_xor_b64 s[50:51], exec, -1
	v_mov_b32_e32 v13, v174
	v_mov_b32_e32 v12, v172
	v_mov_b64_e32 v[6:7], v[4:5]
	v_mov_b64_e32 v[8:9], v[154:155]
	v_mov_b64_e32 v[10:11], v[164:165]
	v_mov_b32_e32 v14, v153
	v_mov_b32_e32 v15, v151

; __device__ __forceinline__ unsigned pk2(float lo, float hi) { return f2bf(lo) | (f2bf(hi) << 16); }
; __device__ __forceinline__ void p0_prologue(const Args& a, LAS unsigned char* lds) {
;     ...
;     { const float* x = a.in[0]; bf16* xb = (bf16*)(ws + WS_XB0); float* ss0 = (float*)(ws + WS_SS0);
;       for (int m = gw; m < M; m += NGW) { const f32x4* xr = (const f32x4*)(x + (size_t)m * D) + lane; u32x2* o8 = (u32x2*)(xb + (size_t)(m >> 8) * 8 * 65536 + (size_t)(m & 255) * 256) + lane; float s = 0.f;
; #pragma unroll
;           for (int j = 0; j < 8; ++j) { const f32x4 v = __builtin_nontemporal_load(xr + 64 * j); s += (v[0] * v[0] + v[1] * v[1]) + (v[2] * v[2] + v[3] * v[3]); u32x2 w; w.x = pk2(v[0], v[1]); w.y = pk2(v[2], v[3]); o8[(size_t)j * (65536 / 4)] = w; }
;           s = wave_sum(s); if (lane < 32) ss0[(size_t)m * 32 + lane] = lane == 0 ? s : 0.f; } }
.Lxcv_last:
	s_waitcnt vmcnt(15)
	v_and_b32_sdwa v5, v27, v22 dst_sel:DWORD dst_unused:UNUSED_PAD src0_sel:WORD_1 src1_sel:DWORD
	v_and_b32_sdwa v7, v25, v22 dst_sel:DWORD dst_unused:UNUSED_PAD src0_sel:WORD_1 src1_sel:DWORD
	v_and_b32_sdwa v6, v26, v22 dst_sel:DWORD dst_unused:UNUSED_PAD src0_sel:WORD_1 src1_sel:DWORD
	v_and_b32_sdwa v23, v24, v22 dst_sel:DWORD dst_unused:UNUSED_PAD src0_sel:WORD_1 src1_sel:DWORD
	v_add3_u32 v5, v27, v5, s18
	v_add3_u32 v7, v25, v7, s18
	v_add3_u32 v23, v24, v23, s18
	v_add3_u32 v6, v26, v6, s18
	v_and_b32_e32 v5, 0xffff0000, v5
	v_and_b32_e32 v7, 0xffff0000, v7
	v_or_b32_sdwa v65, v5, v6 dst_sel:DWORD dst_unused:UNUSED_PAD src0_sel:DWORD src1_sel:WORD_1
	v_or_b32_sdwa v64, v7, v23 dst_sel:DWORD dst_unused:UNUSED_PAD src0_sel:DWORD src1_sel:WORD_1
	v_mul_f32_e32 v3, v25, v25
	v_mul_f32_e32 v4, v27, v27
	global_store_dwordx2 v11, v[64:65], s[12:13] sc1 nt
	v_fmac_f32_e32 v3, v24, v24
	v_fmac_f32_e32 v4, v26, v26
	v_add_f32_e32 v2, v3, v4
	s_mov_b64 exec, s[20:21]
	global_load_dwordx4 v[24:27], v10, s[14:15] offset:-4096 nt
	s_mov_b64 exec, s[22:23]
	s_waitcnt vmcnt(14)
	v_and_b32_sdwa v5, v31, v22 dst_sel:DWORD dst_unused:UNUSED_PAD src0_sel:WORD_1 src1_sel:DWORD
	v_and_b32_sdwa v7, v29, v22 dst_sel:DWORD dst_unused:UNUSED_PAD src0_sel:WORD_1 src1_sel:DWORD
	v_and_b32_sdwa v6, v30, v22 dst_sel:DWORD dst_unused:UNUSED_PAD src0_sel:WORD_1 src1_sel:DWORD
	v_and_b32_sdwa v23, v28, v22 dst_sel:DWORD dst_unused:UNUSED_PAD src0_sel:WORD_1 src1_sel:DWORD
	v_add3_u32 v5, v31, v5, s18
	v_add3_u32 v7, v29, v7, s18
	v_add3_u32 v23, v28, v23, s18
	v_add3_u32 v6, v30, v6, s18
	v_and_b32_e32 v5, 0xffff0000, v5
	v_and_b32_e32 v7, 0xffff0000, v7
	s_add_u32 s24, s12, 0x20000
	s_addc_u32 s25, s13, 0
	v_or_b32_sdwa v67, v5, v6 dst_sel:DWORD dst_unused:UNUSED_PAD src0_sel:DWORD src1_sel:WORD_1
	v_or_b32_sdwa v66, v7, v23 dst_sel:DWORD dst_unused:UNUSED_PAD src0_sel:DWORD src1_sel:WORD_1
	v_mul_f32_e32 v3, v29, v29
	v_mul_f32_e32 v4, v31, v31
	global_store_dwordx2 v11, v[66:67], s[24:25] sc1 nt
	v_fmac_f32_e32 v3, v28, v28
	v_fmac_f32_e32 v4, v30, v30
	v_add_f32_e32 v3, v3, v4
	v_add_f32_e32 v2, v2, v3
	s_mov_b64 exec, s[20:21]
	global_load_dwordx4 v[28:31], v10, s[14:15] offset:-3072 nt
	s_mov_b64 exec, s[22:23]
	s_waitcnt vmcnt(13)
	v_and_b32_sdwa v5, v35, v22 dst_sel:DWORD dst_unused:UNUSED_PAD src0_sel:WORD_1 src1_sel:DWORD
	v_and_b32_sdwa v7, v33, v22 dst_sel:DWORD dst_unused:UNUSED_PAD src0_sel:WORD_1 src1_sel:DWORD
	v_and_b32_sdwa v6, v34, v22 dst_sel:DWORD dst_unused:UNUSED_PAD src0_sel:WORD_1 src1_sel:DWORD
	v_and_b32_sdwa v23, v32, v22 dst_sel:DWORD dst_unused:UNUSED_PAD src0_sel:WORD_1 src1_sel:DWORD
	v_add3_u32 v5, v35, v5, s18
	v_add3_u32 v7, v33, v7, s18
	v_add3_u32 v23, v32, v23, s18
	v_add3_u32 v6, v34, v6, s18
	v_and_b32_e32 v5, 0xffff0000, v5
	v_and_b32_e32 v7, 0xffff0000, v7
	s_add_u32 s24, s12, 0x40000
	s_addc_u32 s25, s13, 0
	v_or_b32_sdwa v69, v5, v6 dst_sel:DWORD dst_unused:UNUSED_PAD src0_sel:DWORD src1_sel:WORD_1
	v_or_b32_sdwa v68, v7, v23 dst_sel:DWORD dst_unused:UNUSED_PAD src0_sel:DWORD src1_sel:WORD_1
	v_mul_f32_e32 v3, v33, v33
	v_mul_f32_e32 v4, v35, v35
	global_store_dwordx2 v11, v[68:69], s[24:25] sc1 nt
	v_fmac_f32_e32 v3, v32, v32
	v_fmac_f32_e32 v4, v34, v34
	v_add_f32_e32 v3, v3, v4
	v_add_f32_e32 v2, v2, v3
	s_mov_b64 exec, s[20:21]
	global_load_dwordx4 v[32:35], v10, s[14:15] offset:-2048 nt
	s_mov_b64 exec, s[22:23]
	s_waitcnt vmcnt(12)
	v_and_b32_sdwa v5, v39, v22 dst_sel:DWORD dst_unused:UNUSED_PAD src0_sel:WORD_1 src1_sel:DWORD
	v_and_b32_sdwa v7, v37, v22 dst_sel:DWORD dst_unused:UNUSED_PAD src0_sel:WORD_1 src1_sel:DWORD
	v_and_b32_sdwa v6, v38, v22 dst_sel:DWORD dst_unused:UNUSED_PAD src0_sel:WORD_1 src1_sel:DWORD
	v_and_b32_sdwa v23, v36, v22 dst_sel:DWORD dst_unused:UNUSED_PAD src0_sel:WORD_1 src1_sel:DWORD
	v_add3_u32 v5, v39, v5, s18
	v_add3_u32 v7, v37, v7, s18
	v_add3_u32 v23, v36, v23, s18
	v_add3_u32 v6, v38, v6, s18
	v_and_b32_e32 v5, 0xffff0000, v5
	v_and_b32_e32 v7, 0xffff0000, v7
	s_add_u32 s24, s12, 0x60000
	s_addc_u32 s25, s13, 0
	v_or_b32_sdwa v71, v5, v6 dst_sel:DWORD dst_unused:UNUSED_PAD src0_sel:DWORD src1_sel:WORD_1
	v_or_b32_sdwa v70, v7, v23 dst_sel:DWORD dst_unused:UNUSED_PAD src0_sel:DWORD src1_sel:WORD_1
	v_mul_f32_e32 v3, v37, v37
	v_mul_f32_e32 v4, v39, v39
	global_store_dwordx2 v11, v[70:71], s[24:25] sc1 nt
	v_fmac_f32_e32 v3, v36, v36
	v_fmac_f32_e32 v4, v38, v38
	v_add_f32_e32 v3, v3, v4
	v_add_f32_e32 v2, v2, v3
	s_mov_b64 exec, s[20:21]
	global_load_dwordx4 v[36:39], v10, s[14:15] offset:-1024 nt
	s_mov_b64 exec, s[22:23]
	s_waitcnt vmcnt(11)
	v_and_b32_sdwa v5, v43, v22 dst_sel:DWORD dst_unused:UNUSED_PAD src0_sel:WORD_1 src1_sel:DWORD
	v_and_b32_sdwa v7, v41, v22 dst_sel:DWORD dst_unused:UNUSED_PAD src0_sel:WORD_1 src1_sel:DWORD
	v_and_b32_sdwa v6, v42, v22 dst_sel:DWORD dst_unused:UNUSED_PAD src0_sel:WORD_1 src1_sel:DWORD
	v_and_b32_sdwa v23, v40, v22 dst_sel:DWORD dst_unused:UNUSED_PAD src0_sel:WORD_1 src1_sel:DWORD
	v_add3_u32 v5, v43, v5, s18
	v_add3_u32 v7, v41, v7, s18
	v_add3_u32 v23, v40, v23, s18
	v_add3_u32 v6, v42, v6, s18
	v_and_b32_e32 v5, 0xffff0000, v5
	v_and_b32_e32 v7, 0xffff0000, v7
	s_add_u32 s24, s12, 0x80000
	s_addc_u32 s25, s13, 0
	v_or_b32_sdwa v73, v5, v6 dst_sel:DWORD dst_unused:UNUSED_PAD src0_sel:DWORD src1_sel:WORD_1
	v_or_b32_sdwa v72, v7, v23 dst_sel:DWORD dst_unused:UNUSED_PAD src0_sel:DWORD src1_sel:WORD_1
	v_mul_f32_e32 v3, v41, v41
	v_mul_f32_e32 v4, v43, v43
	global_store_dwordx2 v11, v[72:73], s[24:25] sc1 nt
	v_fmac_f32_e32 v3, v40, v40
	v_fmac_f32_e32 v4, v42, v42
	v_add_f32_e32 v3, v3, v4
	v_add_f32_e32 v2, v2, v3
	s_mov_b64 exec, s[20:21]
	global_load_dwordx4 v[40:43], v10, s[14:15] offset:0 nt
	s_mov_b64 exec, s[22:23]
	s_waitcnt vmcnt(10)
; __device__ __forceinline__ unsigned pk2(float lo, float hi) { return f2bf(lo) | (f2bf(hi) << 16); }
; __device__ __forceinline__ void p0_prologue(const Args& a, LAS unsigned char* lds) {
;     ...
;     { const float* x = a.in[0]; bf16* xb = (bf16*)(ws + WS_XB0); float* ss0 = (float*)(ws + WS_SS0);
;       for (int m = gw; m < M; m += NGW) { const f32x4* xr = (const f32x4*)(x + (size_t)m * D) + lane; u32x2* o8 = (u32x2*)(xb + (size_t)(m >> 8) * 8 * 65536 + (size_t)(m & 255) * 256) + lane; float s = 0.f;
; #pragma unroll
;           for (int j = 0; j < 8; ++j) { const f32x4 v = __builtin_nontemporal_load(xr + 64 * j); s += (v[0] * v[0] + v[1] * v[1]) + (v[2] * v[2] + v[3] * v[3]); u32x2 w; w.x = pk2(v[0], v[1]); w.y = pk2(v[2], v[3]); o8[(size_t)j * (65536 / 4)] = w; }
;           s = wave_sum(s); if (lane < 32) ss0[(size_t)m * 32 + lane] = lane == 0 ? s : 0.f; } }
	v_and_b32_sdwa v5, v47, v22 dst_sel:DWORD dst_unused:UNUSED_PAD src0_sel:WORD_1 src1_sel:DWORD
	v_and_b32_sdwa v7, v45, v22 dst_sel:DWORD dst_unused:UNUSED_PAD src0_sel:WORD_1 src1_sel:DWORD
	v_and_b32_sdwa v6, v46, v22 dst_sel:DWORD dst_unused:UNUSED_PAD src0_sel:WORD_1 src1_sel:DWORD
	v_and_b32_sdwa v23, v44, v22 dst_sel:DWORD dst_unused:UNUSED_PAD src0_sel:WORD_1 src1_sel:DWORD
	v_add3_u32 v5, v47, v5, s18
	v_add3_u32 v7, v45, v7, s18
	v_add3_u32 v23, v44, v23, s18
	v_add3_u32 v6, v46, v6, s18
	v_and_b32_e32 v5, 0xffff0000, v5
	v_and_b32_e32 v7, 0xffff0000, v7
	s_add_u32 s24, s12, 0xa0000
	s_addc_u32 s25, s13, 0
	v_or_b32_sdwa v75, v5, v6 dst_sel:DWORD dst_unused:UNUSED_PAD src0_sel:DWORD src1_sel:WORD_1
	v_or_b32_sdwa v74, v7, v23 dst_sel:DWORD dst_unused:UNUSED_PAD src0_sel:DWORD src1_sel:WORD_1
	v_mul_f32_e32 v3, v45, v45
	v_mul_f32_e32 v4, v47, v47
	global_store_dwordx2 v11, v[74:75], s[24:25] sc1 nt
	v_fmac_f32_e32 v3, v44, v44
	v_fmac_f32_e32 v4, v46, v46
	v_add_f32_e32 v3, v3, v4
	v_add_f32_e32 v2, v2, v3
	s_mov_b64 exec, s[20:21]
	global_load_dwordx4 v[44:47], v10, s[14:15] offset:1024 nt
	s_mov_b64 exec, s[22:23]
	s_waitcnt vmcnt(9)
	v_and_b32_sdwa v5, v51, v22 dst_sel:DWORD dst_unused:UNUSED_PAD src0_sel:WORD_1 src1_sel:DWORD
	v_and_b32_sdwa v7, v49, v22 dst_sel:DWORD dst_unused:UNUSED_PAD src0_sel:WORD_1 src1_sel:DWORD
	v_and_b32_sdwa v6, v50, v22 dst_sel:DWORD dst_unused:UNUSED_PAD src0_sel:WORD_1 src1_sel:DWORD
	v_and_b32_sdwa v23, v48, v22 dst_sel:DWORD dst_unused:UNUSED_PAD src0_sel:WORD_1 src1_sel:DWORD
	v_add3_u32 v5, v51, v5, s18
	v_add3_u32 v7, v49, v7, s18
	v_add3_u32 v23, v48, v23, s18
	v_add3_u32 v6, v50, v6, s18
	v_and_b32_e32 v5, 0xffff0000, v5
	v_and_b32_e32 v7, 0xffff0000, v7
	s_add_u32 s24, s12, 0xc0000
	s_addc_u32 s25, s13, 0
	v_or_b32_sdwa v77, v5, v6 dst_sel:DWORD dst_unused:UNUSED_PAD src0_sel:DWORD src1_sel:WORD_1
	v_or_b32_sdwa v76, v7, v23 dst_sel:DWORD dst_unused:UNUSED_PAD src0_sel:DWORD src1_sel:WORD_1
	v_mul_f32_e32 v3, v49, v49
	v_mul_f32_e32 v4, v51, v51
	global_store_dwordx2 v11, v[76:77], s[24:25] sc1 nt
	v_fmac_f32_e32 v3, v48, v48
	v_fmac_f32_e32 v4, v50, v50
	v_add_f32_e32 v3, v3, v4
	v_add_f32_e32 v2, v2, v3
	s_mov_b64 exec, s[20:21]
	global_load_dwordx4 v[48:51], v10, s[14:15] offset:2048 nt
	s_mov_b64 exec, s[22:23]
	s_waitcnt vmcnt(8)
	v_and_b32_sdwa v5, v55, v22 dst_sel:DWORD dst_unused:UNUSED_PAD src0_sel:WORD_1 src1_sel:DWORD
	v_and_b32_sdwa v7, v53, v22 dst_sel:DWORD dst_unused:UNUSED_PAD src0_sel:WORD_1 src1_sel:DWORD
	v_and_b32_sdwa v6, v54, v22 dst_sel:DWORD dst_unused:UNUSED_PAD src0_sel:WORD_1 src1_sel:DWORD
	v_and_b32_sdwa v23, v52, v22 dst_sel:DWORD dst_unused:UNUSED_PAD src0_sel:WORD_1 src1_sel:DWORD
	v_add3_u32 v5, v55, v5, s18
	v_add3_u32 v7, v53, v7, s18
	v_add3_u32 v23, v52, v23, s18
	v_add3_u32 v6, v54, v6, s18
	v_and_b32_e32 v5, 0xffff0000, v5
	v_and_b32_e32 v7, 0xffff0000, v7
	s_add_u32 s24, s12, 0xe0000
	s_addc_u32 s25, s13, 0
	v_or_b32_sdwa v79, v5, v6 dst_sel:DWORD dst_unused:UNUSED_PAD src0_sel:DWORD src1_sel:WORD_1
	v_or_b32_sdwa v78, v7, v23 dst_sel:DWORD dst_unused:UNUSED_PAD src0_sel:DWORD src1_sel:WORD_1
	v_mul_f32_e32 v3, v53, v53
	v_mul_f32_e32 v4, v55, v55
	global_store_dwordx2 v11, v[78:79], s[24:25] sc1 nt
	v_fmac_f32_e32 v3, v52, v52
	v_fmac_f32_e32 v4, v54, v54
	v_add_f32_e32 v3, v3, v4
	v_add_f32_e32 v2, v2, v3
	s_mov_b64 exec, s[20:21]
	global_load_dwordx4 v[52:55], v10, s[14:15] offset:3072 nt
	s_mov_b64 exec, s[22:23]
	s_branch .Lxcv_tail
.Lxcv_first:
	s_waitcnt vmcnt(7)
	v_and_b32_sdwa v5, v27, v22 dst_sel:DWORD dst_unused:UNUSED_PAD src0_sel:WORD_1 src1_sel:DWORD
	v_and_b32_sdwa v7, v25, v22 dst_sel:DWORD dst_unused:UNUSED_PAD src0_sel:WORD_1 src1_sel:DWORD
	v_and_b32_sdwa v6, v26, v22 dst_sel:DWORD dst_unused:UNUSED_PAD src0_sel:WORD_1 src1_sel:DWORD
	v_and_b32_sdwa v23, v24, v22 dst_sel:DWORD dst_unused:UNUSED_PAD src0_sel:WORD_1 src1_sel:DWORD
	v_add3_u32 v5, v27, v5, s18
	v_add3_u32 v7, v25, v7, s18
	v_add3_u32 v23, v24, v23, s18
	v_add3_u32 v6, v26, v6, s18
	v_and_b32_e32 v5, 0xffff0000, v5
	v_and_b32_e32 v7, 0xffff0000, v7
	v_or_b32_sdwa v65, v5, v6 dst_sel:DWORD dst_unused:UNUSED_PAD src0_sel:DWORD src1_sel:WORD_1
	v_or_b32_sdwa v64, v7, v23 dst_sel:DWORD dst_unused:UNUSED_PAD src0_sel:DWORD src1_sel:WORD_1
	v_mul_f32_e32 v3, v25, v25
	v_mul_f32_e32 v4, v27, v27
	global_store_dwordx2 v11, v[64:65], s[12:13] sc1 nt
	v_fmac_f32_e32 v3, v24, v24
	v_fmac_f32_e32 v4, v26, v26
	v_add_f32_e32 v2, v3, v4
	s_mov_b64 exec, s[20:21]
	global_load_dwordx4 v[24:27], v10, s[14:15] offset:-4096 nt
	s_mov_b64 exec, s[22:23]
	s_waitcnt vmcnt(7)
	v_and_b32_sdwa v5, v31, v22 dst_sel:DWORD dst_unused:UNUSED_PAD src0_sel:WORD_1 src1_sel:DWORD
	v_and_b32_sdwa v7, v29, v22 dst_sel:DWORD dst_unused:UNUSED_PAD src0_sel:WORD_1 src1_sel:DWORD
	v_and_b32_sdwa v6, v30, v22 dst_sel:DWORD dst_unused:UNUSED_PAD src0_sel:WORD_1 src1_sel:DWORD
	v_and_b32_sdwa v23, v28, v22 dst_sel:DWORD dst_unused:UNUSED_PAD src0_sel:WORD_1 src1_sel:DWORD
	v_add3_u32 v5, v31, v5, s18
	v_add3_u32 v7, v29, v7, s18
	v_add3_u32 v23, v28, v23, s18
	v_add3_u32 v6, v30, v6, s18
	v_and_b32_e32 v5, 0xffff0000, v5
	v_and_b32_e32 v7, 0xffff0000, v7
	s_add_u32 s24, s12, 0x20000
	s_addc_u32 s25, s13, 0
	v_or_b32_sdwa v67, v5, v6 dst_sel:DWORD dst_unused:UNUSED_PAD src0_sel:DWORD src1_sel:WORD_1
	v_or_b32_sdwa v66, v7, v23 dst_sel:DWORD dst_unused:UNUSED_PAD src0_sel:DWORD src1_sel:WORD_1
	v_mul_f32_e32 v3, v29, v29
	v_mul_f32_e32 v4, v31, v31
	global_store_dwordx2 v11, v[66:67], s[24:25] sc1 nt
	v_fmac_f32_e32 v3, v28, v28
	v_fmac_f32_e32 v4, v30, v30
	v_add_f32_e32 v3, v3, v4
	v_add_f32_e32 v2, v2, v3
	s_mov_b64 exec, s[20:21]
	global_load_dwordx4 v[28:31], v10, s[14:15] offset:-3072 nt
	s_mov_b64 exec, s[22:23]
	s_waitcnt vmcnt(7)
; __device__ __forceinline__ unsigned pk2(float lo, float hi) { return f2bf(lo) | (f2bf(hi) << 16); }
; __device__ __forceinline__ void p0_prologue(const Args& a, LAS unsigned char* lds) {
;     ...
;     { const float* x = a.in[0]; bf16* xb = (bf16*)(ws + WS_XB0); float* ss0 = (float*)(ws + WS_SS0);
;       for (int m = gw; m < M; m += NGW) { const f32x4* xr = (const f32x4*)(x + (size_t)m * D) + lane; u32x2* o8 = (u32x2*)(xb + (size_t)(m >> 8) * 8 * 65536 + (size_t)(m & 255) * 256) + lane; float s = 0.f;
; #pragma unroll
;           for (int j = 0; j < 8; ++j) { const f32x4 v = __builtin_nontemporal_load(xr + 64 * j); s += (v[0] * v[0] + v[1] * v[1]) + (v[2] * v[2] + v[3] * v[3]); u32x2 w; w.x = pk2(v[0], v[1]); w.y = pk2(v[2], v[3]); o8[(size_t)j * (65536 / 4)] = w; }
;           s = wave_sum(s); if (lane < 32) ss0[(size_t)m * 32 + lane] = lane == 0 ? s : 0.f; } }
	v_and_b32_sdwa v5, v35, v22 dst_sel:DWORD dst_unused:UNUSED_PAD src0_sel:WORD_1 src1_sel:DWORD
	v_and_b32_sdwa v7, v33, v22 dst_sel:DWORD dst_unused:UNUSED_PAD src0_sel:WORD_1 src1_sel:DWORD
	v_and_b32_sdwa v6, v34, v22 dst_sel:DWORD dst_unused:UNUSED_PAD src0_sel:WORD_1 src1_sel:DWORD
	v_and_b32_sdwa v23, v32, v22 dst_sel:DWORD dst_unused:UNUSED_PAD src0_sel:WORD_1 src1_sel:DWORD
	v_add3_u32 v5, v35, v5, s18
	v_add3_u32 v7, v33, v7, s18
	v_add3_u32 v23, v32, v23, s18
	v_add3_u32 v6, v34, v6, s18
	v_and_b32_e32 v5, 0xffff0000, v5
	v_and_b32_e32 v7, 0xffff0000, v7
	s_add_u32 s24, s12, 0x40000
	s_addc_u32 s25, s13, 0
	v_or_b32_sdwa v69, v5, v6 dst_sel:DWORD dst_unused:UNUSED_PAD src0_sel:DWORD src1_sel:WORD_1
	v_or_b32_sdwa v68, v7, v23 dst_sel:DWORD dst_unused:UNUSED_PAD src0_sel:DWORD src1_sel:WORD_1
	v_mul_f32_e32 v3, v33, v33
	v_mul_f32_e32 v4, v35, v35
	global_store_dwordx2 v11, v[68:69], s[24:25] sc1 nt
	v_fmac_f32_e32 v3, v32, v32
	v_fmac_f32_e32 v4, v34, v34
	v_add_f32_e32 v3, v3, v4
	v_add_f32_e32 v2, v2, v3
	s_mov_b64 exec, s[20:21]
	global_load_dwordx4 v[32:35], v10, s[14:15] offset:-2048 nt
	s_mov_b64 exec, s[22:23]
	s_waitcnt vmcnt(7)
	v_and_b32_sdwa v5, v39, v22 dst_sel:DWORD dst_unused:UNUSED_PAD src0_sel:WORD_1 src1_sel:DWORD
	v_and_b32_sdwa v7, v37, v22 dst_sel:DWORD dst_unused:UNUSED_PAD src0_sel:WORD_1 src1_sel:DWORD
	v_and_b32_sdwa v6, v38, v22 dst_sel:DWORD dst_unused:UNUSED_PAD src0_sel:WORD_1 src1_sel:DWORD
	v_and_b32_sdwa v23, v36, v22 dst_sel:DWORD dst_unused:UNUSED_PAD src0_sel:WORD_1 src1_sel:DWORD
	v_add3_u32 v5, v39, v5, s18
	v_add3_u32 v7, v37, v7, s18
	v_add3_u32 v23, v36, v23, s18
	v_add3_u32 v6, v38, v6, s18
	v_and_b32_e32 v5, 0xffff0000, v5
	v_and_b32_e32 v7, 0xffff0000, v7
	s_add_u32 s24, s12, 0x60000
	s_addc_u32 s25, s13, 0
	v_or_b32_sdwa v71, v5, v6 dst_sel:DWORD dst_unused:UNUSED_PAD src0_sel:DWORD src1_sel:WORD_1
	v_or_b32_sdwa v70, v7, v23 dst_sel:DWORD dst_unused:UNUSED_PAD src0_sel:DWORD src1_sel:WORD_1
	v_mul_f32_e32 v3, v37, v37
	v_mul_f32_e32 v4, v39, v39
	global_store_dwordx2 v11, v[70:71], s[24:25] sc1 nt
	v_fmac_f32_e32 v3, v36, v36
	v_fmac_f32_e32 v4, v38, v38
	v_add_f32_e32 v3, v3, v4
	v_add_f32_e32 v2, v2, v3
	s_mov_b64 exec, s[20:21]
	global_load_dwordx4 v[36:39], v10, s[14:15] offset:-1024 nt
	s_mov_b64 exec, s[22:23]
	s_waitcnt vmcnt(7)
	v_and_b32_sdwa v5, v43, v22 dst_sel:DWORD dst_unused:UNUSED_PAD src0_sel:WORD_1 src1_sel:DWORD
	v_and_b32_sdwa v7, v41, v22 dst_sel:DWORD dst_unused:UNUSED_PAD src0_sel:WORD_1 src1_sel:DWORD
	v_and_b32_sdwa v6, v42, v22 dst_sel:DWORD dst_unused:UNUSED_PAD src0_sel:WORD_1 src1_sel:DWORD
	v_and_b32_sdwa v23, v40, v22 dst_sel:DWORD dst_unused:UNUSED_PAD src0_sel:WORD_1 src1_sel:DWORD
	v_add3_u32 v5, v43, v5, s18
	v_add3_u32 v7, v41, v7, s18
	v_add3_u32 v23, v40, v23, s18
	v_add3_u32 v6, v42, v6, s18
	v_and_b32_e32 v5, 0xffff0000, v5
	v_and_b32_e32 v7, 0xffff0000, v7
	s_add_u32 s24, s12, 0x80000
	s_addc_u32 s25, s13, 0
	v_or_b32_sdwa v73, v5, v6 dst_sel:DWORD dst_unused:UNUSED_PAD src0_sel:DWORD src1_sel:WORD_1
	v_or_b32_sdwa v72, v7, v23 dst_sel:DWORD dst_unused:UNUSED_PAD src0_sel:DWORD src1_sel:WORD_1
	v_mul_f32_e32 v3, v41, v41
	v_mul_f32_e32 v4, v43, v43
	global_store_dwordx2 v11, v[72:73], s[24:25] sc1 nt
	v_fmac_f32_e32 v3, v40, v40
	v_fmac_f32_e32 v4, v42, v42
	v_add_f32_e32 v3, v3, v4
	v_add_f32_e32 v2, v2, v3
	s_mov_b64 exec, s[20:21]
	global_load_dwordx4 v[40:43], v10, s[14:15] offset:0 nt
	s_mov_b64 exec, s[22:23]
	s_waitcnt vmcnt(7)
	v_and_b32_sdwa v5, v47, v22 dst_sel:DWORD dst_unused:UNUSED_PAD src0_sel:WORD_1 src1_sel:DWORD
	v_and_b32_sdwa v7, v45, v22 dst_sel:DWORD dst_unused:UNUSED_PAD src0_sel:WORD_1 src1_sel:DWORD
	v_and_b32_sdwa v6, v46, v22 dst_sel:DWORD dst_unused:UNUSED_PAD src0_sel:WORD_1 src1_sel:DWORD
	v_and_b32_sdwa v23, v44, v22 dst_sel:DWORD dst_unused:UNUSED_PAD src0_sel:WORD_1 src1_sel:DWORD
	v_add3_u32 v5, v47, v5, s18
	v_add3_u32 v7, v45, v7, s18
	v_add3_u32 v23, v44, v23, s18
	v_add3_u32 v6, v46, v6, s18
	v_and_b32_e32 v5, 0xffff0000, v5
	v_and_b32_e32 v7, 0xffff0000, v7
	s_add_u32 s24, s12, 0xa0000
	s_addc_u32 s25, s13, 0
	v_or_b32_sdwa v75, v5, v6 dst_sel:DWORD dst_unused:UNUSED_PAD src0_sel:DWORD src1_sel:WORD_1
	v_or_b32_sdwa v74, v7, v23 dst_sel:DWORD dst_unused:UNUSED_PAD src0_sel:DWORD src1_sel:WORD_1
	v_mul_f32_e32 v3, v45, v45
	v_mul_f32_e32 v4, v47, v47
	global_store_dwordx2 v11, v[74:75], s[24:25] sc1 nt
	v_fmac_f32_e32 v3, v44, v44
	v_fmac_f32_e32 v4, v46, v46
	v_add_f32_e32 v3, v3, v4
	v_add_f32_e32 v2, v2, v3
	s_mov_b64 exec, s[20:21]
	global_load_dwordx4 v[44:47], v10, s[14:15] offset:1024 nt
	s_mov_b64 exec, s[22:23]
	s_waitcnt vmcnt(7)
	v_and_b32_sdwa v5, v51, v22 dst_sel:DWORD dst_unused:UNUSED_PAD src0_sel:WORD_1 src1_sel:DWORD
	v_and_b32_sdwa v7, v49, v22 dst_sel:DWORD dst_unused:UNUSED_PAD src0_sel:WORD_1 src1_sel:DWORD
	v_and_b32_sdwa v6, v50, v22 dst_sel:DWORD dst_unused:UNUSED_PAD src0_sel:WORD_1 src1_sel:DWORD
	v_and_b32_sdwa v23, v48, v22 dst_sel:DWORD dst_unused:UNUSED_PAD src0_sel:WORD_1 src1_sel:DWORD
	v_add3_u32 v5, v51, v5, s18
	v_add3_u32 v7, v49, v7, s18
	v_add3_u32 v23, v48, v23, s18
	v_add3_u32 v6, v50, v6, s18
	v_and_b32_e32 v5, 0xffff0000, v5
	v_and_b32_e32 v7, 0xffff0000, v7
	s_add_u32 s24, s12, 0xc0000
	s_addc_u32 s25, s13, 0
	v_or_b32_sdwa v77, v5, v6 dst_sel:DWORD dst_unused:UNUSED_PAD src0_sel:DWORD src1_sel:WORD_1
	v_or_b32_sdwa v76, v7, v23 dst_sel:DWORD dst_unused:UNUSED_PAD src0_sel:DWORD src1_sel:WORD_1
	v_mul_f32_e32 v3, v49, v49
	v_mul_f32_e32 v4, v51, v51
	global_store_dwordx2 v11, v[76:77], s[24:25] sc1 nt
	v_fmac_f32_e32 v3, v48, v48
	v_fmac_f32_e32 v4, v50, v50
	v_add_f32_e32 v3, v3, v4
	v_add_f32_e32 v2, v2, v3
	s_mov_b64 exec, s[20:21]
	global_load_dwordx4 v[48:51], v10, s[14:15] offset:2048 nt
	s_mov_b64 exec, s[22:23]
	s_waitcnt vmcnt(7)
	v_and_b32_sdwa v5, v55, v22 dst_sel:DWORD dst_unused:UNUSED_PAD src0_sel:WORD_1 src1_sel:DWORD
	v_and_b32_sdwa v7, v53, v22 dst_sel:DWORD dst_unused:UNUSED_PAD src0_sel:WORD_1 src1_sel:DWORD
	v_and_b32_sdwa v6, v54, v22 dst_sel:DWORD dst_unused:UNUSED_PAD src0_sel:WORD_1 src1_sel:DWORD
	v_and_b32_sdwa v23, v52, v22 dst_sel:DWORD dst_unused:UNUSED_PAD src0_sel:WORD_1 src1_sel:DWORD
	v_add3_u32 v5, v55, v5, s18
	v_add3_u32 v7, v53, v7, s18
	v_add3_u32 v23, v52, v23, s18
	v_add3_u32 v6, v54, v6, s18
	v_and_b32_e32 v5, 0xffff0000, v5
	v_and_b32_e32 v7, 0xffff0000, v7
	s_add_u32 s24, s12, 0xe0000
	s_addc_u32 s25, s13, 0
	v_or_b32_sdwa v79, v5, v6 dst_sel:DWORD dst_unused:UNUSED_PAD src0_sel:DWORD src1_sel:WORD_1
	v_or_b32_sdwa v78, v7, v23 dst_sel:DWORD dst_unused:UNUSED_PAD src0_sel:DWORD src1_sel:WORD_1
	v_mul_f32_e32 v3, v53, v53
	v_mul_f32_e32 v4, v55, v55
	global_store_dwordx2 v11, v[78:79], s[24:25] sc1 nt
	v_fmac_f32_e32 v3, v52, v52
	v_fmac_f32_e32 v4, v54, v54
	v_add_f32_e32 v3, v3, v4
	v_add_f32_e32 v2, v2, v3
	s_mov_b64 exec, s[20:21]
	global_load_dwordx4 v[52:55], v10, s[14:15] offset:3072 nt
	s_mov_b64 exec, s[22:23]
	s_branch .Lxcv_tail
; __device__ __forceinline__ unsigned pk2(float lo, float hi) { return f2bf(lo) | (f2bf(hi) << 16); }
; __device__ __forceinline__ void p0_prologue(const Args& a, LAS unsigned char* lds) {
;     ...
;       for (int m = gw; m < M; m += NGW) { const f32x4* xr = (const f32x4*)(x + (size_t)m * D) + lane; u32x2* o8 = (u32x2*)(xb + (size_t)(m >> 8) * 8 * 65536 + (size_t)(m & 255) * 256) + lane; float s = 0.f;
; #pragma unroll
;           for (int j = 0; j < 8; ++j) { const f32x4 v = __builtin_nontemporal_load(xr + 64 * j); s += (v[0] * v[0] + v[1] * v[1]) + (v[2] * v[2] + v[3] * v[3]); u32x2 w; w.x = pk2(v[0], v[1]); w.y = pk2(v[2], v[3]); o8[(size_t)j * (65536 / 4)] = w; }
;           s = wave_sum(s); if (lane < 32) ss0[(size_t)m * 32 + lane] = lane == 0 ? s : 0.f; } }
.Lxcv_mid:
	s_waitcnt vmcnt(15)
	v_and_b32_sdwa v5, v27, v22 dst_sel:DWORD dst_unused:UNUSED_PAD src0_sel:WORD_1 src1_sel:DWORD
	v_and_b32_sdwa v7, v25, v22 dst_sel:DWORD dst_unused:UNUSED_PAD src0_sel:WORD_1 src1_sel:DWORD
	v_and_b32_sdwa v6, v26, v22 dst_sel:DWORD dst_unused:UNUSED_PAD src0_sel:WORD_1 src1_sel:DWORD
	v_and_b32_sdwa v23, v24, v22 dst_sel:DWORD dst_unused:UNUSED_PAD src0_sel:WORD_1 src1_sel:DWORD
	v_add3_u32 v5, v27, v5, s18
	v_add3_u32 v7, v25, v7, s18
	v_add3_u32 v23, v24, v23, s18
	v_add3_u32 v6, v26, v6, s18
	v_and_b32_e32 v5, 0xffff0000, v5
	v_and_b32_e32 v7, 0xffff0000, v7
	v_or_b32_sdwa v65, v5, v6 dst_sel:DWORD dst_unused:UNUSED_PAD src0_sel:DWORD src1_sel:WORD_1
	v_or_b32_sdwa v64, v7, v23 dst_sel:DWORD dst_unused:UNUSED_PAD src0_sel:DWORD src1_sel:WORD_1
	v_mul_f32_e32 v3, v25, v25
	v_mul_f32_e32 v4, v27, v27
	global_store_dwordx2 v11, v[64:65], s[12:13] sc1 nt
	v_fmac_f32_e32 v3, v24, v24
	v_fmac_f32_e32 v4, v26, v26
	v_add_f32_e32 v2, v3, v4
	s_mov_b64 exec, s[20:21]
	global_load_dwordx4 v[24:27], v10, s[14:15] offset:-4096 nt
	s_mov_b64 exec, s[22:23]
	s_waitcnt vmcnt(15)
	v_and_b32_sdwa v5, v31, v22 dst_sel:DWORD dst_unused:UNUSED_PAD src0_sel:WORD_1 src1_sel:DWORD
	v_and_b32_sdwa v7, v29, v22 dst_sel:DWORD dst_unused:UNUSED_PAD src0_sel:WORD_1 src1_sel:DWORD
	v_and_b32_sdwa v6, v30, v22 dst_sel:DWORD dst_unused:UNUSED_PAD src0_sel:WORD_1 src1_sel:DWORD
	v_and_b32_sdwa v23, v28, v22 dst_sel:DWORD dst_unused:UNUSED_PAD src0_sel:WORD_1 src1_sel:DWORD
	v_add3_u32 v5, v31, v5, s18
	v_add3_u32 v7, v29, v7, s18
	v_add3_u32 v23, v28, v23, s18
	v_add3_u32 v6, v30, v6, s18
	v_and_b32_e32 v5, 0xffff0000, v5
	v_and_b32_e32 v7, 0xffff0000, v7
	s_add_u32 s24, s12, 0x20000
	s_addc_u32 s25, s13, 0
	v_or_b32_sdwa v67, v5, v6 dst_sel:DWORD dst_unused:UNUSED_PAD src0_sel:DWORD src1_sel:WORD_1
	v_or_b32_sdwa v66, v7, v23 dst_sel:DWORD dst_unused:UNUSED_PAD src0_sel:DWORD src1_sel:WORD_1
	v_mul_f32_e32 v3, v29, v29
	v_mul_f32_e32 v4, v31, v31
	global_store_dwordx2 v11, v[66:67], s[24:25] sc1 nt
	v_fmac_f32_e32 v3, v28, v28
	v_fmac_f32_e32 v4, v30, v30
	v_add_f32_e32 v3, v3, v4
	v_add_f32_e32 v2, v2, v3
	s_mov_b64 exec, s[20:21]
	global_load_dwordx4 v[28:31], v10, s[14:15] offset:-3072 nt
	s_mov_b64 exec, s[22:23]
	s_waitcnt vmcnt(15)
	v_and_b32_sdwa v5, v35, v22 dst_sel:DWORD dst_unused:UNUSED_PAD src0_sel:WORD_1 src1_sel:DWORD
	v_and_b32_sdwa v7, v33, v22 dst_sel:DWORD dst_unused:UNUSED_PAD src0_sel:WORD_1 src1_sel:DWORD
	v_and_b32_sdwa v6, v34, v22 dst_sel:DWORD dst_unused:UNUSED_PAD src0_sel:WORD_1 src1_sel:DWORD
	v_and_b32_sdwa v23, v32, v22 dst_sel:DWORD dst_unused:UNUSED_PAD src0_sel:WORD_1 src1_sel:DWORD
	v_add3_u32 v5, v35, v5, s18
	v_add3_u32 v7, v33, v7, s18
	v_add3_u32 v23, v32, v23, s18
	v_add3_u32 v6, v34, v6, s18
	v_and_b32_e32 v5, 0xffff0000, v5
	v_and_b32_e32 v7, 0xffff0000, v7
	s_add_u32 s24, s12, 0x40000
	s_addc_u32 s25, s13, 0
	v_or_b32_sdwa v69, v5, v6 dst_sel:DWORD dst_unused:UNUSED_PAD src0_sel:DWORD src1_sel:WORD_1
	v_or_b32_sdwa v68, v7, v23 dst_sel:DWORD dst_unused:UNUSED_PAD src0_sel:DWORD src1_sel:WORD_1
	v_mul_f32_e32 v3, v33, v33
	v_mul_f32_e32 v4, v35, v35
	global_store_dwordx2 v11, v[68:69], s[24:25] sc1 nt
	v_fmac_f32_e32 v3, v32, v32
	v_fmac_f32_e32 v4, v34, v34
	v_add_f32_e32 v3, v3, v4
	v_add_f32_e32 v2, v2, v3
	s_mov_b64 exec, s[20:21]
	global_load_dwordx4 v[32:35], v10, s[14:15] offset:-2048 nt
	s_mov_b64 exec, s[22:23]
	s_waitcnt vmcnt(15)
	v_and_b32_sdwa v5, v39, v22 dst_sel:DWORD dst_unused:UNUSED_PAD src0_sel:WORD_1 src1_sel:DWORD
	v_and_b32_sdwa v7, v37, v22 dst_sel:DWORD dst_unused:UNUSED_PAD src0_sel:WORD_1 src1_sel:DWORD
	v_and_b32_sdwa v6, v38, v22 dst_sel:DWORD dst_unused:UNUSED_PAD src0_sel:WORD_1 src1_sel:DWORD
	v_and_b32_sdwa v23, v36, v22 dst_sel:DWORD dst_unused:UNUSED_PAD src0_sel:WORD_1 src1_sel:DWORD
	v_add3_u32 v5, v39, v5, s18
	v_add3_u32 v7, v37, v7, s18
	v_add3_u32 v23, v36, v23, s18
	v_add3_u32 v6, v38, v6, s18
	v_and_b32_e32 v5, 0xffff0000, v5
	v_and_b32_e32 v7, 0xffff0000, v7
	s_add_u32 s24, s12, 0x60000
	s_addc_u32 s25, s13, 0
	v_or_b32_sdwa v71, v5, v6 dst_sel:DWORD dst_unused:UNUSED_PAD src0_sel:DWORD src1_sel:WORD_1
	v_or_b32_sdwa v70, v7, v23 dst_sel:DWORD dst_unused:UNUSED_PAD src0_sel:DWORD src1_sel:WORD_1
	v_mul_f32_e32 v3, v37, v37
	v_mul_f32_e32 v4, v39, v39
	global_store_dwordx2 v11, v[70:71], s[24:25] sc1 nt
	v_fmac_f32_e32 v3, v36, v36
	v_fmac_f32_e32 v4, v38, v38
	v_add_f32_e32 v3, v3, v4
	v_add_f32_e32 v2, v2, v3
	s_mov_b64 exec, s[20:21]
	global_load_dwordx4 v[36:39], v10, s[14:15] offset:-1024 nt
	s_mov_b64 exec, s[22:23]
	s_waitcnt vmcnt(15)
; __device__ __forceinline__ unsigned pk2(float lo, float hi) { return f2bf(lo) | (f2bf(hi) << 16); }
; __device__ __forceinline__ void p0_prologue(const Args& a, LAS unsigned char* lds) {
;     ...
;       for (int m = gw; m < M; m += NGW) { const f32x4* xr = (const f32x4*)(x + (size_t)m * D) + lane; u32x2* o8 = (u32x2*)(xb + (size_t)(m >> 8) * 8 * 65536 + (size_t)(m & 255) * 256) + lane; float s = 0.f;
; #pragma unroll
;           for (int j = 0; j < 8; ++j) { const f32x4 v = __builtin_nontemporal_load(xr + 64 * j); s += (v[0] * v[0] + v[1] * v[1]) + (v[2] * v[2] + v[3] * v[3]); u32x2 w; w.x = pk2(v[0], v[1]); w.y = pk2(v[2], v[3]); o8[(size_t)j * (65536 / 4)] = w; }
;           s = wave_sum(s); if (lane < 32) ss0[(size_t)m * 32 + lane] = lane == 0 ? s : 0.f; } }
	v_and_b32_sdwa v5, v43, v22 dst_sel:DWORD dst_unused:UNUSED_PAD src0_sel:WORD_1 src1_sel:DWORD
	v_and_b32_sdwa v7, v41, v22 dst_sel:DWORD dst_unused:UNUSED_PAD src0_sel:WORD_1 src1_sel:DWORD
	v_and_b32_sdwa v6, v42, v22 dst_sel:DWORD dst_unused:UNUSED_PAD src0_sel:WORD_1 src1_sel:DWORD
	v_and_b32_sdwa v23, v40, v22 dst_sel:DWORD dst_unused:UNUSED_PAD src0_sel:WORD_1 src1_sel:DWORD
	v_add3_u32 v5, v43, v5, s18
	v_add3_u32 v7, v41, v7, s18
	v_add3_u32 v23, v40, v23, s18
	v_add3_u32 v6, v42, v6, s18
	v_and_b32_e32 v5, 0xffff0000, v5
	v_and_b32_e32 v7, 0xffff0000, v7
	s_add_u32 s24, s12, 0x80000
	s_addc_u32 s25, s13, 0
	v_or_b32_sdwa v73, v5, v6 dst_sel:DWORD dst_unused:UNUSED_PAD src0_sel:DWORD src1_sel:WORD_1
	v_or_b32_sdwa v72, v7, v23 dst_sel:DWORD dst_unused:UNUSED_PAD src0_sel:DWORD src1_sel:WORD_1
	v_mul_f32_e32 v3, v41, v41
	v_mul_f32_e32 v4, v43, v43
	global_store_dwordx2 v11, v[72:73], s[24:25] sc1 nt
	v_fmac_f32_e32 v3, v40, v40
	v_fmac_f32_e32 v4, v42, v42
	v_add_f32_e32 v3, v3, v4
	v_add_f32_e32 v2, v2, v3
	s_mov_b64 exec, s[20:21]
	global_load_dwordx4 v[40:43], v10, s[14:15] offset:0 nt
	s_mov_b64 exec, s[22:23]
	s_waitcnt vmcnt(15)
	v_and_b32_sdwa v5, v47, v22 dst_sel:DWORD dst_unused:UNUSED_PAD src0_sel:WORD_1 src1_sel:DWORD
	v_and_b32_sdwa v7, v45, v22 dst_sel:DWORD dst_unused:UNUSED_PAD src0_sel:WORD_1 src1_sel:DWORD
	v_and_b32_sdwa v6, v46, v22 dst_sel:DWORD dst_unused:UNUSED_PAD src0_sel:WORD_1 src1_sel:DWORD
	v_and_b32_sdwa v23, v44, v22 dst_sel:DWORD dst_unused:UNUSED_PAD src0_sel:WORD_1 src1_sel:DWORD
	v_add3_u32 v5, v47, v5, s18
	v_add3_u32 v7, v45, v7, s18
	v_add3_u32 v23, v44, v23, s18
	v_add3_u32 v6, v46, v6, s18
	v_and_b32_e32 v5, 0xffff0000, v5
	v_and_b32_e32 v7, 0xffff0000, v7
	s_add_u32 s24, s12, 0xa0000
	s_addc_u32 s25, s13, 0
	v_or_b32_sdwa v75, v5, v6 dst_sel:DWORD dst_unused:UNUSED_PAD src0_sel:DWORD src1_sel:WORD_1
	v_or_b32_sdwa v74, v7, v23 dst_sel:DWORD dst_unused:UNUSED_PAD src0_sel:DWORD src1_sel:WORD_1
	v_mul_f32_e32 v3, v45, v45
	v_mul_f32_e32 v4, v47, v47
	global_store_dwordx2 v11, v[74:75], s[24:25] sc1 nt
	v_fmac_f32_e32 v3, v44, v44
	v_fmac_f32_e32 v4, v46, v46
	v_add_f32_e32 v3, v3, v4
	v_add_f32_e32 v2, v2, v3
	s_mov_b64 exec, s[20:21]
	global_load_dwordx4 v[44:47], v10, s[14:15] offset:1024 nt
	s_mov_b64 exec, s[22:23]
	s_waitcnt vmcnt(15)
	v_and_b32_sdwa v5, v51, v22 dst_sel:DWORD dst_unused:UNUSED_PAD src0_sel:WORD_1 src1_sel:DWORD
	v_and_b32_sdwa v7, v49, v22 dst_sel:DWORD dst_unused:UNUSED_PAD src0_sel:WORD_1 src1_sel:DWORD
	v_and_b32_sdwa v6, v50, v22 dst_sel:DWORD dst_unused:UNUSED_PAD src0_sel:WORD_1 src1_sel:DWORD
	v_and_b32_sdwa v23, v48, v22 dst_sel:DWORD dst_unused:UNUSED_PAD src0_sel:WORD_1 src1_sel:DWORD
	v_add3_u32 v5, v51, v5, s18
	v_add3_u32 v7, v49, v7, s18
	v_add3_u32 v23, v48, v23, s18
	v_add3_u32 v6, v50, v6, s18
	v_and_b32_e32 v5, 0xffff0000, v5
	v_and_b32_e32 v7, 0xffff0000, v7
	s_add_u32 s24, s12, 0xc0000
	s_addc_u32 s25, s13, 0
	v_or_b32_sdwa v77, v5, v6 dst_sel:DWORD dst_unused:UNUSED_PAD src0_sel:DWORD src1_sel:WORD_1
	v_or_b32_sdwa v76, v7, v23 dst_sel:DWORD dst_unused:UNUSED_PAD src0_sel:DWORD src1_sel:WORD_1
	v_mul_f32_e32 v3, v49, v49
	v_mul_f32_e32 v4, v51, v51
	global_store_dwordx2 v11, v[76:77], s[24:25] sc1 nt
	v_fmac_f32_e32 v3, v48, v48
	v_fmac_f32_e32 v4, v50, v50
	v_add_f32_e32 v3, v3, v4
	v_add_f32_e32 v2, v2, v3
	s_mov_b64 exec, s[20:21]
	global_load_dwordx4 v[48:51], v10, s[14:15] offset:2048 nt
	s_mov_b64 exec, s[22:23]
	s_waitcnt vmcnt(15)
	v_and_b32_sdwa v5, v55, v22 dst_sel:DWORD dst_unused:UNUSED_PAD src0_sel:WORD_1 src1_sel:DWORD
	v_and_b32_sdwa v7, v53, v22 dst_sel:DWORD dst_unused:UNUSED_PAD src0_sel:WORD_1 src1_sel:DWORD
	v_and_b32_sdwa v6, v54, v22 dst_sel:DWORD dst_unused:UNUSED_PAD src0_sel:WORD_1 src1_sel:DWORD
	v_and_b32_sdwa v23, v52, v22 dst_sel:DWORD dst_unused:UNUSED_PAD src0_sel:WORD_1 src1_sel:DWORD
	v_add3_u32 v5, v55, v5, s18
	v_add3_u32 v7, v53, v7, s18
	v_add3_u32 v23, v52, v23, s18
	v_add3_u32 v6, v54, v6, s18
	v_and_b32_e32 v5, 0xffff0000, v5
	v_and_b32_e32 v7, 0xffff0000, v7
	s_add_u32 s24, s12, 0xe0000
	s_addc_u32 s25, s13, 0
	v_or_b32_sdwa v79, v5, v6 dst_sel:DWORD dst_unused:UNUSED_PAD src0_sel:DWORD src1_sel:WORD_1
	v_or_b32_sdwa v78, v7, v23 dst_sel:DWORD dst_unused:UNUSED_PAD src0_sel:DWORD src1_sel:WORD_1
	v_mul_f32_e32 v3, v53, v53
	v_mul_f32_e32 v4, v55, v55
	global_store_dwordx2 v11, v[78:79], s[24:25] sc1 nt
	v_fmac_f32_e32 v3, v52, v52
	v_fmac_f32_e32 v4, v54, v54
	v_add_f32_e32 v3, v3, v4
	v_add_f32_e32 v2, v2, v3
	s_mov_b64 exec, s[20:21]
	global_load_dwordx4 v[52:55], v10, s[14:15] offset:3072 nt
	s_mov_b64 exec, s[22:23]

; __device__ __forceinline__ unsigned pk2(float lo, float hi) { return f2bf(lo) | (f2bf(hi) << 16); }
; __device__ __forceinline__ void p0_prologue(const Args& a, LAS unsigned char* lds) {
;     ...
;     { const float* p = a.in[1]; bf16* pb = (bf16*)(ws + WS_PB); const size_t n8 = (size_t)2 * M * PLE / 8;
;       for (size_t i = (size_t)blockIdx.x * 512 + tid; i < n8; i += (size_t)G * 512) { const f32x4 v0 = *(const f32x4*)(p + i * 8), v1 = *(const f32x4*)(p + i * 8 + 4);
;           u32x4 w; w.x = pk2(v0[0], v0[1]); w.y = pk2(v0[2], v0[3]); w.z = pk2(v1[0], v1[1]); w.w = pk2(v1[2], v1[3]); *(u32x4*)(pb + i * 8) = w; } }
.Lpcv_grp:
	s_cmpk_lt_u32 s100, 0x800
	s_cbranch_scc0 .Lpcv_rest
	v_lshl_add_u64 v[56:57], v[4:5], 0, s[6:7]
	v_lshl_add_u64 v[58:59], v[56:57], 0, s[6:7]
	v_lshl_add_u64 v[60:61], v[58:59], 0, s[6:7]
	global_load_dwordx4 v[24:27], v[4:5], off offset:-16 nt
	global_load_dwordx4 v[28:31], v[4:5], off nt
	global_load_dwordx4 v[32:35], v[56:57], off offset:-16 nt
	global_load_dwordx4 v[36:39], v[56:57], off nt
	global_load_dwordx4 v[40:43], v[58:59], off offset:-16 nt
	global_load_dwordx4 v[44:47], v[58:59], off nt
	global_load_dwordx4 v[48:51], v[60:61], off offset:-16 nt
	global_load_dwordx4 v[52:55], v[60:61], off nt
	v_lshl_add_u64 v[4:5], v[60:61], 0, s[6:7]
	v_lshl_add_u64 v[62:63], v[6:7], 0, s[8:9]
	v_lshl_add_u64 v[64:65], v[62:63], 0, s[8:9]
	v_lshl_add_u64 v[66:67], v[64:65], 0, s[8:9]
	v_lshl_add_u64 v[2:3], v[2:3], 0, s[98:99]
	s_waitcnt vmcnt(6)
	v_cvt_pk_bf16_f32 v24, v24, v25
	v_cvt_pk_bf16_f32 v25, v26, v27
	v_cvt_pk_bf16_f32 v26, v28, v29
	v_cvt_pk_bf16_f32 v27, v30, v31
	global_store_dwordx4 v[6:7], v[24:27], off sc1 nt
	s_waitcnt vmcnt(5)
	v_cvt_pk_bf16_f32 v32, v32, v33
	v_cvt_pk_bf16_f32 v33, v34, v35
	v_cvt_pk_bf16_f32 v34, v36, v37
	v_cvt_pk_bf16_f32 v35, v38, v39
	global_store_dwordx4 v[62:63], v[32:35], off sc1 nt
	s_waitcnt vmcnt(4)
	v_cvt_pk_bf16_f32 v40, v40, v41
	v_cvt_pk_bf16_f32 v41, v42, v43
	v_cvt_pk_bf16_f32 v42, v44, v45
	v_cvt_pk_bf16_f32 v43, v46, v47
	global_store_dwordx4 v[64:65], v[40:43], off sc1 nt
	s_waitcnt vmcnt(3)
	v_cvt_pk_bf16_f32 v48, v48, v49
	v_cvt_pk_bf16_f32 v49, v50, v51
	v_cvt_pk_bf16_f32 v50, v52, v53
	v_cvt_pk_bf16_f32 v51, v54, v55
	global_store_dwordx4 v[66:67], v[48:51], off sc1 nt
	v_lshl_add_u64 v[6:7], v[66:67], 0, s[8:9]
	s_add_u32 s100, s100, s101
	s_branch .Lpcv_grp

; __device__ __forceinline__ unsigned pk2(float lo, float hi) { return f2bf(lo) | (f2bf(hi) << 16); }
; __device__ __forceinline__ void p0_prologue(const Args& a, LAS unsigned char* lds) {
;     ...
;     { const float* p = a.in[1]; bf16* pb = (bf16*)(ws + WS_PB); const size_t n8 = (size_t)2 * M * PLE / 8;
;       for (size_t i = (size_t)blockIdx.x * 512 + tid; i < n8; i += (size_t)G * 512) { const f32x4 v0 = *(const f32x4*)(p + i * 8), v1 = *(const f32x4*)(p + i * 8 + 4);
;           u32x4 w; w.x = pk2(v0[0], v0[1]); w.y = pk2(v0[2], v0[3]); w.z = pk2(v1[0], v1[1]); w.w = pk2(v1[2], v1[3]); *(u32x4*)(pb + i * 8) = w; } }
.LBB0_326:
	global_load_dwordx4 v[8:11], v[4:5], off offset:-16
	global_load_dwordx4 v[12:15], v[4:5], off
	v_lshl_add_u64 v[2:3], v[2:3], 0, s[4:5]
	v_cmp_lt_u64_e32 vcc, s[12:13], v[2:3]
	v_lshl_add_u64 v[4:5], v[4:5], 0, s[6:7]
	s_or_b64 s[10:11], vcc, s[10:11]
	s_waitcnt vmcnt(1)
	v_bfe_u32 v1, v8, 16, 1
	v_bfe_u32 v16, v9, 16, 1
	v_bfe_u32 v17, v10, 16, 1
	v_bfe_u32 v18, v11, 16, 1
	s_waitcnt vmcnt(0)
	v_bfe_u32 v19, v12, 16, 1
	v_bfe_u32 v20, v13, 16, 1
	v_bfe_u32 v21, v14, 16, 1
	v_bfe_u32 v22, v15, 16, 1
	v_add3_u32 v1, v8, v1, s3
	v_add3_u32 v8, v9, v16, s3
	v_add3_u32 v9, v10, v17, s3
	v_add3_u32 v10, v11, v18, s3
	v_add3_u32 v11, v12, v19, s3
	v_add3_u32 v12, v13, v20, s3
	v_add3_u32 v13, v14, v21, s3
	v_add3_u32 v14, v15, v22, s3
	v_lshrrev_b32_e32 v1, 16, v1
	v_lshrrev_b32_e32 v9, 16, v9
	v_lshrrev_b32_e32 v11, 16, v11
	v_lshrrev_b32_e32 v13, 16, v13
	v_and_or_b32 v8, v8, s14, v1
	v_and_or_b32 v9, v10, s14, v9
	v_and_or_b32 v10, v12, s14, v11
	v_and_or_b32 v11, v14, s14, v13
	global_store_dwordx4 v[6:7], v[8:11], off sc1 nt
	v_lshl_add_u64 v[6:7], v[6:7], 0, s[8:9]
	s_andn2_b64 exec, exec, s[10:11]
	s_cbranch_execnz .LBB0_326
